# remeasure reversed-priority GEMM variant
# baseline (speedup 1.0000x reference)
; #define PG8_STAGE(bufoff, gbase, voff) do { _Pragma("unroll") for (int _i = 0; _i < 2; ++_i) \
;         __builtin_amdgcn_global_load_lds((const unsigned*)((const char*)(gbase) + (voff)[_i]), (PG8_LAS unsigned*)(lds + (bufoff) + ldsw + _i * 8192), 16, 0, 0); } while (0)
; #define PG8_LDA(dst, b, h) do { _Pragma("unroll") for (int m = 0; m < 4; ++m) _Pragma("unroll") for (int k = 0; k < 2; ++k) dst[m][k] = *(const PG8_LAS bf16x8*)(lds + PG8_SA(b, h) + aoff + m * 2048 + k * 1024); } while (0)
; #define PG8_LDB(dst, b, h) do { _Pragma("unroll") for (int n = 0; n < 2; ++n) _Pragma("unroll") for (int k = 0; k < 2; ++k) dst[n][k] = *(const PG8_LAS bf16x8*)(lds + PG8_SB(b, h) + boff + n * 2048 + k * 1024); } while (0)
; #define PG8_MMA(ai, bj, At, Bt) do { __builtin_amdgcn_s_setprio(1); _Pragma("unroll") for (int m = 0; m < 4; ++m) _Pragma("unroll") for (int n = 0; n < 2; ++n) _Pragma("unroll") for (int k = 0; k < 2; ++k) \
;         acc[ai][bj][m][n] = __builtin_amdgcn_mfma_f32_16x16x32_bf16(Bt[n][k], At[m][k], acc[ai][bj][m][n], 0, 0, 0); __builtin_amdgcn_s_setprio(0); } while (0)
; #define PG8_WAIT_V(n) asm volatile("s_waitcnt vmcnt(" #n ")" ::: "memory")
; template <class Epi, class Sched, bool ALIGN_EPI = false, bool SP2 = false>
; __device__ __forceinline__ void gemm_phase(PG8_LAS unsigned char* lds, const Gemm g, const Sched& S, const Epi& E) {
;     ...
;             PG8_LDB(B0, 0, 0); PG8_LDB(B1, 0, 1); PG8_SCHED; PG8_LDA(At, 0, 0); PG8_STAGE(PG8_SA(1, 1), a1 + hstep, voffA);
;             PG8_WAIT_V(8); PG8_WAIT_L(0); PG8_BAR; PG8_MMA(0, 0, At, B0); PG8_MMA(0, 1, At, B1); PG8_BAR; PG8_SCHED;
;             PG8_LDA(At, 0, 1); PG8_STAGE(PG8_SB(0, 0), b2, voffB); PG8_STAGE(PG8_SB(0, 1), b2 + hstep, voffB); PG8_STAGE(PG8_SA(0, 0), a2, voffA);
;             PG8_WAIT_V(8); PG8_WAIT_L(0); PG8_BAR; PG8_MMA(1, 0, At, B0); PG8_MMA(1, 1, At, B1); PG8_BAR; PG8_SCHED;
;             PG8_LDB(B0, 1, 0); PG8_LDB(B1, 1, 1); PG8_SCHED; PG8_LDA(At, 1, 0); PG8_STAGE(PG8_SA(0, 1), a2 + hstep, voffA);
;             PG8_WAIT_V(8); PG8_WAIT_L(0); PG8_BAR; PG8_MMA(0, 0, At, B0); PG8_MMA(0, 1, At, B1); PG8_BAR; PG8_SCHED;
;             PG8_LDA(At, 1, 1); PG8_STAGE(PG8_SB(1, 0), b3, voffB); PG8_STAGE(PG8_SB(1, 1), b3 + hstep, voffB); PG8_STAGE(PG8_SA(1, 0), a3, voffA);
;             PG8_WAIT_V(8); PG8_WAIT_L(0); PG8_BAR; PG8_MMA(1, 0, At, B0); PG8_MMA(1, 1, At, B1); PG8_BAR; PG8_SCHED;
.LBB0_132:
	ds_read_b128 v[152:155], v171
	ds_read_b128 v[176:179], v171 offset:1024
	ds_read_b128 v[180:183], v171 offset:2048
	ds_read_b128 v[184:187], v171 offset:3072
	ds_read_b128 v[188:191], v172
	ds_read_b128 v[192:195], v172 offset:1024
	ds_read_b128 v[198:201], v172 offset:2048
	ds_read_b128 v[202:205], v172 offset:3072
	s_add_u32 s46, s2, 0xfff00080
	s_addc_u32 s47, s3, -1
	s_cmp_eq_u32 s82, 60
	s_cselect_b32 s49, s35, s47
	s_cselect_b32 s48, s43, s46
	s_cselect_b32 s47, s17, s81
	s_cselect_b32 s46, s79, s80
	v_lshl_add_u64 v[156:157], s[2:3], 0, v[144:145]
	s_add_i32 m0, s45, 0xc000
	ds_read_b128 v[206:209], v173
	ds_read_b128 v[210:213], v173 offset:1024
	ds_read_b128 v[214:217], v173 offset:2048
	ds_read_b128 v[218:221], v173 offset:3072
	ds_read_b128 v[222:225], v173 offset:4096
	ds_read_b128 v[226:229], v173 offset:5120
	ds_read_b128 v[230:233], v173 offset:6144
	ds_read_b128 v[234:237], v173 offset:7168
	global_load_lds_dwordx4 v[156:157], off
	v_lshl_add_u64 v[156:157], s[2:3], 0, v[146:147]
	s_add_i32 m0, s45, 0xe000
	s_nop 0
	global_load_lds_dwordx4 v[156:157], off
	s_waitcnt vmcnt(8)
	s_waitcnt lgkmcnt(0)
	s_setprio 0
	s_barrier
	v_mfma_f32_16x16x32_bf16 v[126:129], v[152:155], v[206:209], v[126:129]
	v_mfma_f32_16x16x32_bf16 v[122:125], v[180:183], v[206:209], v[122:125]
	v_mfma_f32_16x16x32_bf16 v[110:113], v[152:155], v[214:217], v[110:113]
	v_mfma_f32_16x16x32_bf16 v[106:109], v[180:183], v[214:217], v[106:109]
	v_mfma_f32_16x16x32_bf16 v[94:97], v[152:155], v[222:225], v[94:97]
	v_mfma_f32_16x16x32_bf16 v[90:93], v[180:183], v[222:225], v[90:93]
	v_mfma_f32_16x16x32_bf16 v[78:81], v[152:155], v[230:233], v[78:81]
	v_mfma_f32_16x16x32_bf16 v[74:77], v[180:183], v[230:233], v[74:77]
	v_mfma_f32_16x16x32_bf16 v[126:129], v[176:179], v[210:213], v[126:129]
	v_mfma_f32_16x16x32_bf16 v[122:125], v[184:187], v[210:213], v[122:125]
	v_mfma_f32_16x16x32_bf16 v[110:113], v[176:179], v[218:221], v[110:113]
	v_mfma_f32_16x16x32_bf16 v[106:109], v[184:187], v[218:221], v[106:109]
	v_mfma_f32_16x16x32_bf16 v[94:97], v[176:179], v[226:229], v[94:97]
	v_mfma_f32_16x16x32_bf16 v[90:93], v[184:187], v[226:229], v[90:93]
	v_mfma_f32_16x16x32_bf16 v[78:81], v[176:179], v[234:237], v[78:81]
	v_mfma_f32_16x16x32_bf16 v[74:77], v[184:187], v[234:237], v[74:77]
	s_setprio 0
	s_setprio 0
	v_mfma_f32_16x16x32_bf16 v[118:121], v[188:191], v[206:209], v[118:121]
	v_mfma_f32_16x16x32_bf16 v[114:117], v[198:201], v[206:209], v[114:117]
	v_mfma_f32_16x16x32_bf16 v[102:105], v[188:191], v[214:217], v[102:105]
	v_mfma_f32_16x16x32_bf16 v[98:101], v[198:201], v[214:217], v[98:101]
	v_mfma_f32_16x16x32_bf16 v[86:89], v[188:191], v[222:225], v[86:89]
	v_mfma_f32_16x16x32_bf16 v[82:85], v[198:201], v[222:225], v[82:85]
	v_mfma_f32_16x16x32_bf16 v[70:73], v[188:191], v[230:233], v[70:73]
	v_mfma_f32_16x16x32_bf16 v[66:69], v[198:201], v[230:233], v[66:69]
	v_mfma_f32_16x16x32_bf16 v[118:121], v[192:195], v[210:213], v[118:121]
	v_mfma_f32_16x16x32_bf16 v[114:117], v[202:205], v[210:213], v[114:117]
	v_mfma_f32_16x16x32_bf16 v[102:105], v[192:195], v[218:221], v[102:105]
	v_mfma_f32_16x16x32_bf16 v[98:101], v[202:205], v[218:221], v[98:101]
	v_mfma_f32_16x16x32_bf16 v[86:89], v[192:195], v[226:229], v[86:89]
	v_mfma_f32_16x16x32_bf16 v[82:85], v[202:205], v[226:229], v[82:85]
	v_mfma_f32_16x16x32_bf16 v[70:73], v[192:195], v[234:237], v[70:73]
	v_mfma_f32_16x16x32_bf16 v[66:69], v[202:205], v[234:237], v[66:69]
	s_setprio 1
	s_barrier
	s_add_i32 s83, s74, s55
	v_lshl_add_u64 v[156:157], s[46:47], 0, v[132:133]
	s_mov_b32 m0, s83
	ds_read_b128 v[206:209], v173 offset:16384
	ds_read_b128 v[210:213], v173 offset:17408
	ds_read_b128 v[214:217], v173 offset:18432
	ds_read_b128 v[218:221], v173 offset:19456
	ds_read_b128 v[222:225], v173 offset:20480
	ds_read_b128 v[226:229], v173 offset:21504
	ds_read_b128 v[230:233], v173 offset:22528
	ds_read_b128 v[234:237], v173 offset:23552
	global_load_lds_dwordx4 v[156:157], off
	s_add_i32 m0, s83, 0x2000
	s_add_u32 s84, s46, 0x100000
	v_lshl_add_u64 v[238:239], s[46:47], 0, v[136:137]
	s_addc_u32 s85, s47, 0
	s_add_i32 s83, s75, s55
	global_load_lds_dwordx4 v[238:239], off
	v_lshl_add_u64 v[240:241], s[84:85], 0, v[132:133]
	s_mov_b32 m0, s83
	v_lshl_add_u64 v[242:243], s[48:49], 0, v[134:135]
	global_load_lds_dwordx4 v[240:241], off
	v_lshl_add_u64 v[240:241], s[84:85], 0, v[136:137]
	s_add_i32 m0, s83, 0x2000
	s_nop 0
	global_load_lds_dwordx4 v[240:241], off
	v_lshl_add_u64 v[240:241], s[48:49], 0, v[130:131]
	s_mov_b32 m0, s45
	s_nop 0
	global_load_lds_dwordx4 v[240:241], off
	s_mov_b32 m0, s56
	s_nop 0
	global_load_lds_dwordx4 v[242:243], off
	s_waitcnt vmcnt(8)
	s_waitcnt lgkmcnt(0)
	s_setprio 0
	s_barrier
; #define PG8_STAGE(bufoff, gbase, voff) do { _Pragma("unroll") for (int _i = 0; _i < 2; ++_i) \
;         __builtin_amdgcn_global_load_lds((const unsigned*)((const char*)(gbase) + (voff)[_i]), (PG8_LAS unsigned*)(lds + (bufoff) + ldsw + _i * 8192), 16, 0, 0); } while (0)
; #define PG8_LDA(dst, b, h) do { _Pragma("unroll") for (int m = 0; m < 4; ++m) _Pragma("unroll") for (int k = 0; k < 2; ++k) dst[m][k] = *(const PG8_LAS bf16x8*)(lds + PG8_SA(b, h) + aoff + m * 2048 + k * 1024); } while (0)
; #define PG8_LDB(dst, b, h) do { _Pragma("unroll") for (int n = 0; n < 2; ++n) _Pragma("unroll") for (int k = 0; k < 2; ++k) dst[n][k] = *(const PG8_LAS bf16x8*)(lds + PG8_SB(b, h) + boff + n * 2048 + k * 1024); } while (0)
; #define PG8_MMA(ai, bj, At, Bt) do { __builtin_amdgcn_s_setprio(1); _Pragma("unroll") for (int m = 0; m < 4; ++m) _Pragma("unroll") for (int n = 0; n < 2; ++n) _Pragma("unroll") for (int k = 0; k < 2; ++k) \
;         acc[ai][bj][m][n] = __builtin_amdgcn_mfma_f32_16x16x32_bf16(Bt[n][k], At[m][k], acc[ai][bj][m][n], 0, 0, 0); __builtin_amdgcn_s_setprio(0); } while (0)
; #define PG8_WAIT_V(n) asm volatile("s_waitcnt vmcnt(" #n ")" ::: "memory")
; template <class Epi, class Sched, bool ALIGN_EPI = false, bool SP2 = false>
; __device__ __forceinline__ void gemm_phase(PG8_LAS unsigned char* lds, const Gemm g, const Sched& S, const Epi& E) {
;     ...
;             PG8_LDB(B0, 0, 0); PG8_LDB(B1, 0, 1); PG8_SCHED; PG8_LDA(At, 0, 0); PG8_STAGE(PG8_SA(1, 1), a1 + hstep, voffA);
;             PG8_WAIT_V(8); PG8_WAIT_L(0); PG8_BAR; PG8_MMA(0, 0, At, B0); PG8_MMA(0, 1, At, B1); PG8_BAR; PG8_SCHED;
;             PG8_LDA(At, 0, 1); PG8_STAGE(PG8_SB(0, 0), b2, voffB); PG8_STAGE(PG8_SB(0, 1), b2 + hstep, voffB); PG8_STAGE(PG8_SA(0, 0), a2, voffA);
;             PG8_WAIT_V(8); PG8_WAIT_L(0); PG8_BAR; PG8_MMA(1, 0, At, B0); PG8_MMA(1, 1, At, B1); PG8_BAR; PG8_SCHED;
;             PG8_LDB(B0, 1, 0); PG8_LDB(B1, 1, 1); PG8_SCHED; PG8_LDA(At, 1, 0); PG8_STAGE(PG8_SA(0, 1), a2 + hstep, voffA);
;             PG8_WAIT_V(8); PG8_WAIT_L(0); PG8_BAR; PG8_MMA(0, 0, At, B0); PG8_MMA(0, 1, At, B1); PG8_BAR; PG8_SCHED;
;             PG8_LDA(At, 1, 1); PG8_STAGE(PG8_SB(1, 0), b3, voffB); PG8_STAGE(PG8_SB(1, 1), b3 + hstep, voffB); PG8_STAGE(PG8_SA(1, 0), a3, voffA);
;             PG8_WAIT_V(8); PG8_WAIT_L(0); PG8_BAR; PG8_MMA(1, 0, At, B0); PG8_MMA(1, 1, At, B1); PG8_BAR; PG8_SCHED;
	v_mfma_f32_16x16x32_bf16 v[62:65], v[152:155], v[206:209], v[62:65]
	v_mfma_f32_16x16x32_bf16 v[58:61], v[180:183], v[206:209], v[58:61]
	v_mfma_f32_16x16x32_bf16 v[46:49], v[152:155], v[214:217], v[46:49]
	v_mfma_f32_16x16x32_bf16 v[42:45], v[180:183], v[214:217], v[42:45]
	v_mfma_f32_16x16x32_bf16 v[30:33], v[152:155], v[222:225], v[30:33]
	v_mfma_f32_16x16x32_bf16 v[26:29], v[180:183], v[222:225], v[26:29]
	v_mfma_f32_16x16x32_bf16 v[14:17], v[152:155], v[230:233], v[14:17]
	v_mfma_f32_16x16x32_bf16 v[10:13], v[180:183], v[230:233], v[10:13]
	v_mfma_f32_16x16x32_bf16 v[62:65], v[176:179], v[210:213], v[62:65]
	v_mfma_f32_16x16x32_bf16 v[58:61], v[184:187], v[210:213], v[58:61]
	v_mfma_f32_16x16x32_bf16 v[46:49], v[176:179], v[218:221], v[46:49]
	v_mfma_f32_16x16x32_bf16 v[42:45], v[184:187], v[218:221], v[42:45]
	v_mfma_f32_16x16x32_bf16 v[30:33], v[176:179], v[226:229], v[30:33]
	v_mfma_f32_16x16x32_bf16 v[26:29], v[184:187], v[226:229], v[26:29]
	v_mfma_f32_16x16x32_bf16 v[14:17], v[176:179], v[234:237], v[14:17]
	v_mfma_f32_16x16x32_bf16 v[10:13], v[184:187], v[234:237], v[10:13]
	s_setprio 0
	s_setprio 0
	v_mfma_f32_16x16x32_bf16 v[54:57], v[188:191], v[206:209], v[54:57]
	v_mfma_f32_16x16x32_bf16 v[50:53], v[198:201], v[206:209], v[50:53]
	v_mfma_f32_16x16x32_bf16 v[38:41], v[188:191], v[214:217], v[38:41]
	v_mfma_f32_16x16x32_bf16 v[34:37], v[198:201], v[214:217], v[34:37]
	v_mfma_f32_16x16x32_bf16 v[22:25], v[188:191], v[222:225], v[22:25]
	v_mfma_f32_16x16x32_bf16 v[18:21], v[198:201], v[222:225], v[18:21]
	v_mfma_f32_16x16x32_bf16 v[6:9], v[188:191], v[230:233], v[6:9]
	v_mfma_f32_16x16x32_bf16 v[2:5], v[198:201], v[230:233], v[2:5]
	v_mfma_f32_16x16x32_bf16 v[54:57], v[192:195], v[210:213], v[54:57]
	v_mfma_f32_16x16x32_bf16 v[50:53], v[202:205], v[210:213], v[50:53]
	v_mfma_f32_16x16x32_bf16 v[38:41], v[192:195], v[218:221], v[38:41]
	v_mfma_f32_16x16x32_bf16 v[34:37], v[202:205], v[218:221], v[34:37]
	v_mfma_f32_16x16x32_bf16 v[22:25], v[192:195], v[226:229], v[22:25]
	v_mfma_f32_16x16x32_bf16 v[18:21], v[202:205], v[226:229], v[18:21]
	v_mfma_f32_16x16x32_bf16 v[6:9], v[192:195], v[234:237], v[6:9]
	v_mfma_f32_16x16x32_bf16 v[2:5], v[202:205], v[234:237], v[2:5]
	s_setprio 1
	s_barrier
	s_add_i32 s83, 0, 0x18000
	v_add_u32_e32 v149, s83, v167
	s_add_i32 s84, 0, 0x1c000
	ds_read_b128 v[152:155], v149
	ds_read_b128 v[176:179], v149 offset:1024
	ds_read_b128 v[180:183], v149 offset:2048
	ds_read_b128 v[184:187], v149 offset:3072
	v_add_u32_e32 v149, s84, v167
	ds_read_b128 v[188:191], v149
	ds_read_b128 v[192:195], v149 offset:1024
	ds_read_b128 v[198:201], v149 offset:2048
	ds_read_b128 v[202:205], v149 offset:3072
	s_add_u32 s48, s48, 0x100000
	s_addc_u32 s49, s49, 0
	s_mov_b32 m0, s57
	v_lshl_add_u64 v[244:245], s[48:49], 0, v[130:131]
	ds_read_b128 v[206:209], v173 offset:32768
	ds_read_b128 v[210:213], v173 offset:33792
	ds_read_b128 v[214:217], v173 offset:34816
	ds_read_b128 v[218:221], v173 offset:35840
	ds_read_b128 v[222:225], v173 offset:36864
	ds_read_b128 v[226:229], v173 offset:37888
	ds_read_b128 v[230:233], v173 offset:38912
	ds_read_b128 v[234:237], v173 offset:39936
	global_load_lds_dwordx4 v[244:245], off
	v_lshl_add_u64 v[244:245], s[48:49], 0, v[134:135]
	s_mov_b32 m0, s58
	s_nop 0
	global_load_lds_dwordx4 v[244:245], off
	s_waitcnt vmcnt(8)
	s_waitcnt lgkmcnt(0)
	s_setprio 0
	s_barrier
	v_mfma_f32_16x16x32_bf16 v[126:129], v[152:155], v[206:209], v[126:129]
	v_mfma_f32_16x16x32_bf16 v[122:125], v[180:183], v[206:209], v[122:125]
	v_mfma_f32_16x16x32_bf16 v[110:113], v[152:155], v[214:217], v[110:113]
	v_mfma_f32_16x16x32_bf16 v[106:109], v[180:183], v[214:217], v[106:109]
	v_mfma_f32_16x16x32_bf16 v[94:97], v[152:155], v[222:225], v[94:97]
	v_mfma_f32_16x16x32_bf16 v[90:93], v[180:183], v[222:225], v[90:93]
	v_mfma_f32_16x16x32_bf16 v[78:81], v[152:155], v[230:233], v[78:81]
	v_mfma_f32_16x16x32_bf16 v[74:77], v[180:183], v[230:233], v[74:77]
	v_mfma_f32_16x16x32_bf16 v[126:129], v[176:179], v[210:213], v[126:129]
	v_mfma_f32_16x16x32_bf16 v[122:125], v[184:187], v[210:213], v[122:125]
	v_mfma_f32_16x16x32_bf16 v[110:113], v[176:179], v[218:221], v[110:113]
	v_mfma_f32_16x16x32_bf16 v[106:109], v[184:187], v[218:221], v[106:109]
	v_mfma_f32_16x16x32_bf16 v[94:97], v[176:179], v[226:229], v[94:97]
	v_mfma_f32_16x16x32_bf16 v[90:93], v[184:187], v[226:229], v[90:93]
	v_mfma_f32_16x16x32_bf16 v[78:81], v[176:179], v[234:237], v[78:81]
	v_mfma_f32_16x16x32_bf16 v[74:77], v[184:187], v[234:237], v[74:77]
	s_setprio 0
	s_setprio 0
	v_mfma_f32_16x16x32_bf16 v[118:121], v[188:191], v[206:209], v[118:121]
	v_mfma_f32_16x16x32_bf16 v[114:117], v[198:201], v[206:209], v[114:117]
	v_mfma_f32_16x16x32_bf16 v[102:105], v[188:191], v[214:217], v[102:105]
	v_mfma_f32_16x16x32_bf16 v[98:101], v[198:201], v[214:217], v[98:101]
	v_mfma_f32_16x16x32_bf16 v[86:89], v[188:191], v[222:225], v[86:89]
	v_mfma_f32_16x16x32_bf16 v[82:85], v[198:201], v[222:225], v[82:85]
	v_mfma_f32_16x16x32_bf16 v[70:73], v[188:191], v[230:233], v[70:73]
	v_mfma_f32_16x16x32_bf16 v[66:69], v[198:201], v[230:233], v[66:69]
	v_mfma_f32_16x16x32_bf16 v[118:121], v[192:195], v[210:213], v[118:121]
	v_mfma_f32_16x16x32_bf16 v[114:117], v[202:205], v[210:213], v[114:117]
	v_mfma_f32_16x16x32_bf16 v[102:105], v[192:195], v[218:221], v[102:105]
	v_mfma_f32_16x16x32_bf16 v[98:101], v[202:205], v[218:221], v[98:101]
	v_mfma_f32_16x16x32_bf16 v[86:89], v[192:195], v[226:229], v[86:89]
	v_mfma_f32_16x16x32_bf16 v[82:85], v[202:205], v[226:229], v[82:85]
	v_mfma_f32_16x16x32_bf16 v[70:73], v[192:195], v[234:237], v[70:73]
	v_mfma_f32_16x16x32_bf16 v[66:69], v[202:205], v[234:237], v[66:69]
	s_setprio 1
	s_barrier
; #define PG8_STAGE(bufoff, gbase, voff) do { _Pragma("unroll") for (int _i = 0; _i < 2; ++_i) \
;         __builtin_amdgcn_global_load_lds((const unsigned*)((const char*)(gbase) + (voff)[_i]), (PG8_LAS unsigned*)(lds + (bufoff) + ldsw + _i * 8192), 16, 0, 0); } while (0)
; #define PG8_LDA(dst, b, h) do { _Pragma("unroll") for (int m = 0; m < 4; ++m) _Pragma("unroll") for (int k = 0; k < 2; ++k) dst[m][k] = *(const PG8_LAS bf16x8*)(lds + PG8_SA(b, h) + aoff + m * 2048 + k * 1024); } while (0)
; #define PG8_MMA(ai, bj, At, Bt) do { __builtin_amdgcn_s_setprio(1); _Pragma("unroll") for (int m = 0; m < 4; ++m) _Pragma("unroll") for (int n = 0; n < 2; ++n) _Pragma("unroll") for (int k = 0; k < 2; ++k) \
;         acc[ai][bj][m][n] = __builtin_amdgcn_mfma_f32_16x16x32_bf16(Bt[n][k], At[m][k], acc[ai][bj][m][n], 0, 0, 0); __builtin_amdgcn_s_setprio(0); } while (0)
; #define PG8_WAIT_V(n) asm volatile("s_waitcnt vmcnt(" #n ")" ::: "memory")
; #define PG8_WAIT_L(n) asm volatile("s_waitcnt lgkmcnt(" #n ")" ::: "memory")
; #define PG8_BAR __builtin_amdgcn_s_barrier()
; #define PG8_SCHED __builtin_amdgcn_sched_barrier(0)
; template <class Epi, class Sched, bool ALIGN_EPI = false, bool SP2 = false>
; __device__ __forceinline__ void gemm_phase(PG8_LAS unsigned char* lds, const Gemm g, const Sched& S, const Epi& E) {
;     ...
;             PG8_LDA(At, 1, 1); PG8_STAGE(PG8_SB(1, 0), b3, voffB); PG8_STAGE(PG8_SB(1, 1), b3 + hstep, voffB); PG8_STAGE(PG8_SA(1, 0), a3, voffA);
;             PG8_WAIT_V(8); PG8_WAIT_L(0); PG8_BAR; PG8_MMA(1, 0, At, B0); PG8_MMA(1, 1, At, B1); PG8_BAR; PG8_SCHED;
;     ...
;         if constexpr (ALIGN_EPI) { if (wr == 0) PG8_BAR; }
	s_add_i32 s48, s83, s55
	v_lshl_add_u64 v[156:157], v[156:157], 0, s[10:11]
	s_mov_b32 m0, s48
	ds_read_b128 v[206:209], v173 offset:49152
	ds_read_b128 v[210:213], v173 offset:50176
	ds_read_b128 v[214:217], v173 offset:51200
	ds_read_b128 v[218:221], v173 offset:52224
	ds_read_b128 v[222:225], v173 offset:53248
	ds_read_b128 v[226:229], v173 offset:54272
	ds_read_b128 v[230:233], v173 offset:55296
	ds_read_b128 v[234:237], v173 offset:56320
	global_load_lds_dwordx4 v[156:157], off
	s_add_i32 m0, s48, 0x2000
	s_add_u32 s46, s46, 0x100080
	v_lshl_add_u64 v[156:157], v[238:239], 0, s[10:11]
	s_addc_u32 s47, s47, 0
	s_add_i32 s48, s84, s55
	global_load_lds_dwordx4 v[156:157], off
	v_lshl_add_u64 v[156:157], s[46:47], 0, v[132:133]
	s_mov_b32 m0, s48
	s_nop 0
	global_load_lds_dwordx4 v[156:157], off
	v_lshl_add_u64 v[156:157], s[46:47], 0, v[136:137]
	s_add_i32 m0, s48, 0x2000
	s_nop 0
	global_load_lds_dwordx4 v[156:157], off
	v_lshl_add_u64 v[156:157], v[240:241], 0, s[10:11]
	s_mov_b32 m0, s63
	s_nop 0
	global_load_lds_dwordx4 v[156:157], off
	v_lshl_add_u64 v[156:157], v[242:243], 0, s[10:11]
	s_mov_b32 m0, s70
	s_nop 0
	global_load_lds_dwordx4 v[156:157], off
	s_waitcnt vmcnt(8)
	s_waitcnt lgkmcnt(0)
	s_setprio 0
	s_barrier
	v_mfma_f32_16x16x32_bf16 v[62:65], v[152:155], v[206:209], v[62:65]
	v_mfma_f32_16x16x32_bf16 v[58:61], v[180:183], v[206:209], v[58:61]
	v_mfma_f32_16x16x32_bf16 v[46:49], v[152:155], v[214:217], v[46:49]
	v_mfma_f32_16x16x32_bf16 v[42:45], v[180:183], v[214:217], v[42:45]
	v_mfma_f32_16x16x32_bf16 v[30:33], v[152:155], v[222:225], v[30:33]
	v_mfma_f32_16x16x32_bf16 v[26:29], v[180:183], v[222:225], v[26:29]
	v_mfma_f32_16x16x32_bf16 v[14:17], v[152:155], v[230:233], v[14:17]
	v_mfma_f32_16x16x32_bf16 v[10:13], v[180:183], v[230:233], v[10:13]
	v_mfma_f32_16x16x32_bf16 v[62:65], v[176:179], v[210:213], v[62:65]
	v_mfma_f32_16x16x32_bf16 v[58:61], v[184:187], v[210:213], v[58:61]
	v_mfma_f32_16x16x32_bf16 v[46:49], v[176:179], v[218:221], v[46:49]
	v_mfma_f32_16x16x32_bf16 v[42:45], v[184:187], v[218:221], v[42:45]
	v_mfma_f32_16x16x32_bf16 v[30:33], v[176:179], v[226:229], v[30:33]
	v_mfma_f32_16x16x32_bf16 v[26:29], v[184:187], v[226:229], v[26:29]
	v_mfma_f32_16x16x32_bf16 v[14:17], v[176:179], v[234:237], v[14:17]
	v_mfma_f32_16x16x32_bf16 v[10:13], v[184:187], v[234:237], v[10:13]
	s_setprio 0
	s_setprio 0
	v_mfma_f32_16x16x32_bf16 v[54:57], v[188:191], v[206:209], v[54:57]
	v_mfma_f32_16x16x32_bf16 v[50:53], v[198:201], v[206:209], v[50:53]
	v_mfma_f32_16x16x32_bf16 v[38:41], v[188:191], v[214:217], v[38:41]
	v_mfma_f32_16x16x32_bf16 v[34:37], v[198:201], v[214:217], v[34:37]
	v_mfma_f32_16x16x32_bf16 v[22:25], v[188:191], v[222:225], v[22:25]
	v_mfma_f32_16x16x32_bf16 v[18:21], v[198:201], v[222:225], v[18:21]
	v_mfma_f32_16x16x32_bf16 v[6:9], v[188:191], v[230:233], v[6:9]
	v_mfma_f32_16x16x32_bf16 v[2:5], v[198:201], v[230:233], v[2:5]
	v_mfma_f32_16x16x32_bf16 v[54:57], v[192:195], v[210:213], v[54:57]
	v_mfma_f32_16x16x32_bf16 v[50:53], v[202:205], v[210:213], v[50:53]
	v_mfma_f32_16x16x32_bf16 v[38:41], v[192:195], v[218:221], v[38:41]
	v_mfma_f32_16x16x32_bf16 v[34:37], v[202:205], v[218:221], v[34:37]
	v_mfma_f32_16x16x32_bf16 v[22:25], v[192:195], v[226:229], v[22:25]
	v_mfma_f32_16x16x32_bf16 v[18:21], v[202:205], v[226:229], v[18:21]
	v_mfma_f32_16x16x32_bf16 v[6:9], v[192:195], v[234:237], v[6:9]
	v_mfma_f32_16x16x32_bf16 v[2:5], v[202:205], v[234:237], v[2:5]
	s_setprio 1
	s_barrier
	s_add_i32 s82, s82, 2
	s_add_u32 s2, s2, 0x100
	s_addc_u32 s3, s3, 0
	s_add_u32 s80, s80, 0x100
	s_addc_u32 s81, s81, 0
	s_cmp_gt_u32 s82, 61
	s_cbranch_scc0 .LBB0_132
	s_and_b64 vcc, exec, s[12:13]
	s_cbranch_vccz .LBB0_135
	s_barrier

; #define PG8_STAGE(bufoff, gbase, voff) do { _Pragma("unroll") for (int _i = 0; _i < 2; ++_i) \
;         __builtin_amdgcn_global_load_lds((const unsigned*)((const char*)(gbase) + (voff)[_i]), (PG8_LAS unsigned*)(lds + (bufoff) + ldsw + _i * 8192), 16, 0, 0); } while (0)
; #define PG8_LDA(dst, b, h) do { _Pragma("unroll") for (int m = 0; m < 4; ++m) _Pragma("unroll") for (int k = 0; k < 2; ++k) dst[m][k] = *(const PG8_LAS bf16x8*)(lds + PG8_SA(b, h) + aoff + m * 2048 + k * 1024); } while (0)
; #define PG8_LDB(dst, b, h) do { _Pragma("unroll") for (int n = 0; n < 2; ++n) _Pragma("unroll") for (int k = 0; k < 2; ++k) dst[n][k] = *(const PG8_LAS bf16x8*)(lds + PG8_SB(b, h) + boff + n * 2048 + k * 1024); } while (0)
; #define PG8_MMA(ai, bj, At, Bt) do { __builtin_amdgcn_s_setprio(1); _Pragma("unroll") for (int m = 0; m < 4; ++m) _Pragma("unroll") for (int n = 0; n < 2; ++n) _Pragma("unroll") for (int k = 0; k < 2; ++k) \
;         acc[ai][bj][m][n] = __builtin_amdgcn_mfma_f32_16x16x32_bf16(Bt[n][k], At[m][k], acc[ai][bj][m][n], 0, 0, 0); __builtin_amdgcn_s_setprio(0); } while (0)
; #define PG8_WAIT_V(n) asm volatile("s_waitcnt vmcnt(" #n ")" ::: "memory")
; template <class Epi, class Sched, bool ALIGN_EPI = false, bool SP2 = false>
; __device__ __forceinline__ void gemm_phase(PG8_LAS unsigned char* lds, const Gemm g, const Sched& S, const Epi& E) {
;     ...
;             PG8_LDB(B0, 0, 0); PG8_LDB(B1, 0, 1); PG8_SCHED; PG8_LDA(At, 0, 0); PG8_STAGE(PG8_SA(1, 1), a1 + hstep, voffA);
;             PG8_WAIT_V(8); PG8_WAIT_L(0); PG8_BAR; PG8_MMA(0, 0, At, B0); PG8_MMA(0, 1, At, B1); PG8_BAR; PG8_SCHED;
;             PG8_LDA(At, 0, 1); PG8_STAGE(PG8_SB(0, 0), b2, voffB); PG8_STAGE(PG8_SB(0, 1), b2 + hstep, voffB); PG8_STAGE(PG8_SA(0, 0), a2, voffA);
;             PG8_WAIT_V(8); PG8_WAIT_L(0); PG8_BAR; PG8_MMA(1, 0, At, B0); PG8_MMA(1, 1, At, B1); PG8_BAR; PG8_SCHED;
;             PG8_LDB(B0, 1, 0); PG8_LDB(B1, 1, 1); PG8_SCHED; PG8_LDA(At, 1, 0); PG8_STAGE(PG8_SA(0, 1), a2 + hstep, voffA);
;             PG8_WAIT_V(8); PG8_WAIT_L(0); PG8_BAR; PG8_MMA(0, 0, At, B0); PG8_MMA(0, 1, At, B1); PG8_BAR; PG8_SCHED;
;             PG8_LDA(At, 1, 1); PG8_STAGE(PG8_SB(1, 0), b3, voffB); PG8_STAGE(PG8_SB(1, 1), b3 + hstep, voffB); PG8_STAGE(PG8_SA(1, 0), a3, voffA);
;             PG8_WAIT_V(8); PG8_WAIT_L(0); PG8_BAR; PG8_MMA(1, 0, At, B0); PG8_MMA(1, 1, At, B1); PG8_BAR; PG8_SCHED;
.LBB0_217:
	ds_read_b128 v[152:155], v159
	ds_read_b128 v[168:171], v159 offset:1024
	ds_read_b128 v[172:175], v159 offset:2048
	ds_read_b128 v[176:179], v159 offset:3072
	ds_read_b128 v[180:183], v160
	ds_read_b128 v[184:187], v160 offset:1024
	ds_read_b128 v[188:191], v160 offset:2048
	ds_read_b128 v[192:195], v160 offset:3072
	s_add_u32 s46, s44, 0xfff00080
	s_addc_u32 s47, s45, -1
	s_cmp_eq_u32 s80, 60
	s_cselect_b32 s49, s3, s47
	s_cselect_b32 s48, s35, s46
	s_cselect_b32 s47, s17, s79
	s_cselect_b32 s46, s43, s78
	v_lshl_add_u64 v[156:157], s[44:45], 0, v[144:145]
	s_add_i32 m0, s56, 0xc000
	ds_read_b128 v[198:201], v161
	ds_read_b128 v[202:205], v161 offset:1024
	ds_read_b128 v[206:209], v161 offset:2048
	ds_read_b128 v[210:213], v161 offset:3072
	ds_read_b128 v[214:217], v161 offset:4096
	ds_read_b128 v[218:221], v161 offset:5120
	ds_read_b128 v[222:225], v161 offset:6144
	ds_read_b128 v[226:229], v161 offset:7168
	global_load_lds_dwordx4 v[156:157], off
	v_lshl_add_u64 v[156:157], s[44:45], 0, v[146:147]
	s_add_i32 m0, s56, 0xe000
	s_nop 0
	global_load_lds_dwordx4 v[156:157], off
	s_waitcnt vmcnt(8)
	s_waitcnt lgkmcnt(0)
	s_setprio 0
	s_barrier
	v_mfma_f32_16x16x32_bf16 v[126:129], v[152:155], v[198:201], v[126:129]
	v_mfma_f32_16x16x32_bf16 v[122:125], v[172:175], v[198:201], v[122:125]
	v_mfma_f32_16x16x32_bf16 v[110:113], v[152:155], v[206:209], v[110:113]
	v_mfma_f32_16x16x32_bf16 v[106:109], v[172:175], v[206:209], v[106:109]
	v_mfma_f32_16x16x32_bf16 v[94:97], v[152:155], v[214:217], v[94:97]
	v_mfma_f32_16x16x32_bf16 v[90:93], v[172:175], v[214:217], v[90:93]
	v_mfma_f32_16x16x32_bf16 v[78:81], v[152:155], v[222:225], v[78:81]
	v_mfma_f32_16x16x32_bf16 v[74:77], v[172:175], v[222:225], v[74:77]
	v_mfma_f32_16x16x32_bf16 v[126:129], v[168:171], v[202:205], v[126:129]
	v_mfma_f32_16x16x32_bf16 v[122:125], v[176:179], v[202:205], v[122:125]
	v_mfma_f32_16x16x32_bf16 v[110:113], v[168:171], v[210:213], v[110:113]
	v_mfma_f32_16x16x32_bf16 v[106:109], v[176:179], v[210:213], v[106:109]
	v_mfma_f32_16x16x32_bf16 v[94:97], v[168:171], v[218:221], v[94:97]
	v_mfma_f32_16x16x32_bf16 v[90:93], v[176:179], v[218:221], v[90:93]
	v_mfma_f32_16x16x32_bf16 v[78:81], v[168:171], v[226:229], v[78:81]
	v_mfma_f32_16x16x32_bf16 v[74:77], v[176:179], v[226:229], v[74:77]
	s_setprio 0
	s_setprio 0
	v_mfma_f32_16x16x32_bf16 v[118:121], v[180:183], v[198:201], v[118:121]
	v_mfma_f32_16x16x32_bf16 v[114:117], v[188:191], v[198:201], v[114:117]
	v_mfma_f32_16x16x32_bf16 v[102:105], v[180:183], v[206:209], v[102:105]
	v_mfma_f32_16x16x32_bf16 v[98:101], v[188:191], v[206:209], v[98:101]
	v_mfma_f32_16x16x32_bf16 v[86:89], v[180:183], v[214:217], v[86:89]
	v_mfma_f32_16x16x32_bf16 v[82:85], v[188:191], v[214:217], v[82:85]
	v_mfma_f32_16x16x32_bf16 v[70:73], v[180:183], v[222:225], v[70:73]
	v_mfma_f32_16x16x32_bf16 v[66:69], v[188:191], v[222:225], v[66:69]
	v_mfma_f32_16x16x32_bf16 v[118:121], v[184:187], v[202:205], v[118:121]
	v_mfma_f32_16x16x32_bf16 v[114:117], v[192:195], v[202:205], v[114:117]
	v_mfma_f32_16x16x32_bf16 v[102:105], v[184:187], v[210:213], v[102:105]
	v_mfma_f32_16x16x32_bf16 v[98:101], v[192:195], v[210:213], v[98:101]
	v_mfma_f32_16x16x32_bf16 v[86:89], v[184:187], v[218:221], v[86:89]
	v_mfma_f32_16x16x32_bf16 v[82:85], v[192:195], v[218:221], v[82:85]
	v_mfma_f32_16x16x32_bf16 v[70:73], v[184:187], v[226:229], v[70:73]
	v_mfma_f32_16x16x32_bf16 v[66:69], v[192:195], v[226:229], v[66:69]
	s_setprio 1
	s_barrier
	s_add_i32 s81, s73, s55
	v_lshl_add_u64 v[156:157], s[46:47], 0, v[132:133]
	s_mov_b32 m0, s81
	ds_read_b128 v[198:201], v161 offset:16384
	ds_read_b128 v[202:205], v161 offset:17408
	ds_read_b128 v[206:209], v161 offset:18432
	ds_read_b128 v[210:213], v161 offset:19456
	ds_read_b128 v[214:217], v161 offset:20480
	ds_read_b128 v[218:221], v161 offset:21504
	ds_read_b128 v[222:225], v161 offset:22528
	ds_read_b128 v[226:229], v161 offset:23552
	global_load_lds_dwordx4 v[156:157], off
	s_add_i32 m0, s81, 0x2000
	s_add_u32 s82, s46, 0x100000
	v_lshl_add_u64 v[230:231], s[46:47], 0, v[136:137]
	s_addc_u32 s83, s47, 0
	s_add_i32 s81, s74, s55
	global_load_lds_dwordx4 v[230:231], off
	v_lshl_add_u64 v[232:233], s[82:83], 0, v[132:133]
	s_mov_b32 m0, s81
	v_lshl_add_u64 v[234:235], s[48:49], 0, v[134:135]
	global_load_lds_dwordx4 v[232:233], off
	v_lshl_add_u64 v[232:233], s[82:83], 0, v[136:137]
	s_add_i32 m0, s81, 0x2000
	s_nop 0
	global_load_lds_dwordx4 v[232:233], off
	v_lshl_add_u64 v[232:233], s[48:49], 0, v[130:131]
	s_mov_b32 m0, s56
	s_nop 0
	global_load_lds_dwordx4 v[232:233], off
	s_mov_b32 m0, s57
	s_nop 0
	global_load_lds_dwordx4 v[234:235], off
	s_waitcnt vmcnt(8)
	s_waitcnt lgkmcnt(0)
	s_setprio 0
	s_barrier
; #define PG8_STAGE(bufoff, gbase, voff) do { _Pragma("unroll") for (int _i = 0; _i < 2; ++_i) \
;         __builtin_amdgcn_global_load_lds((const unsigned*)((const char*)(gbase) + (voff)[_i]), (PG8_LAS unsigned*)(lds + (bufoff) + ldsw + _i * 8192), 16, 0, 0); } while (0)
; #define PG8_LDA(dst, b, h) do { _Pragma("unroll") for (int m = 0; m < 4; ++m) _Pragma("unroll") for (int k = 0; k < 2; ++k) dst[m][k] = *(const PG8_LAS bf16x8*)(lds + PG8_SA(b, h) + aoff + m * 2048 + k * 1024); } while (0)
; #define PG8_LDB(dst, b, h) do { _Pragma("unroll") for (int n = 0; n < 2; ++n) _Pragma("unroll") for (int k = 0; k < 2; ++k) dst[n][k] = *(const PG8_LAS bf16x8*)(lds + PG8_SB(b, h) + boff + n * 2048 + k * 1024); } while (0)
; #define PG8_MMA(ai, bj, At, Bt) do { __builtin_amdgcn_s_setprio(1); _Pragma("unroll") for (int m = 0; m < 4; ++m) _Pragma("unroll") for (int n = 0; n < 2; ++n) _Pragma("unroll") for (int k = 0; k < 2; ++k) \
;         acc[ai][bj][m][n] = __builtin_amdgcn_mfma_f32_16x16x32_bf16(Bt[n][k], At[m][k], acc[ai][bj][m][n], 0, 0, 0); __builtin_amdgcn_s_setprio(0); } while (0)
; #define PG8_WAIT_V(n) asm volatile("s_waitcnt vmcnt(" #n ")" ::: "memory")
; template <class Epi, class Sched, bool ALIGN_EPI = false, bool SP2 = false>
; __device__ __forceinline__ void gemm_phase(PG8_LAS unsigned char* lds, const Gemm g, const Sched& S, const Epi& E) {
;     ...
;             PG8_LDB(B0, 0, 0); PG8_LDB(B1, 0, 1); PG8_SCHED; PG8_LDA(At, 0, 0); PG8_STAGE(PG8_SA(1, 1), a1 + hstep, voffA);
;             PG8_WAIT_V(8); PG8_WAIT_L(0); PG8_BAR; PG8_MMA(0, 0, At, B0); PG8_MMA(0, 1, At, B1); PG8_BAR; PG8_SCHED;
;             PG8_LDA(At, 0, 1); PG8_STAGE(PG8_SB(0, 0), b2, voffB); PG8_STAGE(PG8_SB(0, 1), b2 + hstep, voffB); PG8_STAGE(PG8_SA(0, 0), a2, voffA);
;             PG8_WAIT_V(8); PG8_WAIT_L(0); PG8_BAR; PG8_MMA(1, 0, At, B0); PG8_MMA(1, 1, At, B1); PG8_BAR; PG8_SCHED;
;             PG8_LDB(B0, 1, 0); PG8_LDB(B1, 1, 1); PG8_SCHED; PG8_LDA(At, 1, 0); PG8_STAGE(PG8_SA(0, 1), a2 + hstep, voffA);
;             PG8_WAIT_V(8); PG8_WAIT_L(0); PG8_BAR; PG8_MMA(0, 0, At, B0); PG8_MMA(0, 1, At, B1); PG8_BAR; PG8_SCHED;
;             PG8_LDA(At, 1, 1); PG8_STAGE(PG8_SB(1, 0), b3, voffB); PG8_STAGE(PG8_SB(1, 1), b3 + hstep, voffB); PG8_STAGE(PG8_SA(1, 0), a3, voffA);
;             PG8_WAIT_V(8); PG8_WAIT_L(0); PG8_BAR; PG8_MMA(1, 0, At, B0); PG8_MMA(1, 1, At, B1); PG8_BAR; PG8_SCHED;
	v_mfma_f32_16x16x32_bf16 v[62:65], v[152:155], v[198:201], v[62:65]
	v_mfma_f32_16x16x32_bf16 v[58:61], v[172:175], v[198:201], v[58:61]
	v_mfma_f32_16x16x32_bf16 v[46:49], v[152:155], v[206:209], v[46:49]
	v_mfma_f32_16x16x32_bf16 v[42:45], v[172:175], v[206:209], v[42:45]
	v_mfma_f32_16x16x32_bf16 v[30:33], v[152:155], v[214:217], v[30:33]
	v_mfma_f32_16x16x32_bf16 v[26:29], v[172:175], v[214:217], v[26:29]
	v_mfma_f32_16x16x32_bf16 v[14:17], v[152:155], v[222:225], v[14:17]
	v_mfma_f32_16x16x32_bf16 v[10:13], v[172:175], v[222:225], v[10:13]
	v_mfma_f32_16x16x32_bf16 v[62:65], v[168:171], v[202:205], v[62:65]
	v_mfma_f32_16x16x32_bf16 v[58:61], v[176:179], v[202:205], v[58:61]
	v_mfma_f32_16x16x32_bf16 v[46:49], v[168:171], v[210:213], v[46:49]
	v_mfma_f32_16x16x32_bf16 v[42:45], v[176:179], v[210:213], v[42:45]
	v_mfma_f32_16x16x32_bf16 v[30:33], v[168:171], v[218:221], v[30:33]
	v_mfma_f32_16x16x32_bf16 v[26:29], v[176:179], v[218:221], v[26:29]
	v_mfma_f32_16x16x32_bf16 v[14:17], v[168:171], v[226:229], v[14:17]
	v_mfma_f32_16x16x32_bf16 v[10:13], v[176:179], v[226:229], v[10:13]
	s_setprio 0
	s_setprio 0
	v_mfma_f32_16x16x32_bf16 v[54:57], v[180:183], v[198:201], v[54:57]
	v_mfma_f32_16x16x32_bf16 v[50:53], v[188:191], v[198:201], v[50:53]
	v_mfma_f32_16x16x32_bf16 v[38:41], v[180:183], v[206:209], v[38:41]
	v_mfma_f32_16x16x32_bf16 v[34:37], v[188:191], v[206:209], v[34:37]
	v_mfma_f32_16x16x32_bf16 v[22:25], v[180:183], v[214:217], v[22:25]
	v_mfma_f32_16x16x32_bf16 v[18:21], v[188:191], v[214:217], v[18:21]
	v_mfma_f32_16x16x32_bf16 v[6:9], v[180:183], v[222:225], v[6:9]
	v_mfma_f32_16x16x32_bf16 v[2:5], v[188:191], v[222:225], v[2:5]
	v_mfma_f32_16x16x32_bf16 v[54:57], v[184:187], v[202:205], v[54:57]
	v_mfma_f32_16x16x32_bf16 v[50:53], v[192:195], v[202:205], v[50:53]
	v_mfma_f32_16x16x32_bf16 v[38:41], v[184:187], v[210:213], v[38:41]
	v_mfma_f32_16x16x32_bf16 v[34:37], v[192:195], v[210:213], v[34:37]
	v_mfma_f32_16x16x32_bf16 v[22:25], v[184:187], v[218:221], v[22:25]
	v_mfma_f32_16x16x32_bf16 v[18:21], v[192:195], v[218:221], v[18:21]
	v_mfma_f32_16x16x32_bf16 v[6:9], v[184:187], v[226:229], v[6:9]
	v_mfma_f32_16x16x32_bf16 v[2:5], v[192:195], v[226:229], v[2:5]
	s_setprio 1
	s_barrier
	s_add_i32 s81, 0, 0x18000
	v_add_u32_e32 v149, s81, v164
	s_add_i32 s82, 0, 0x1c000
	ds_read_b128 v[152:155], v149
	ds_read_b128 v[168:171], v149 offset:1024
	ds_read_b128 v[172:175], v149 offset:2048
	ds_read_b128 v[176:179], v149 offset:3072
	v_add_u32_e32 v149, s82, v164
	ds_read_b128 v[180:183], v149
	ds_read_b128 v[184:187], v149 offset:1024
	ds_read_b128 v[188:191], v149 offset:2048
	ds_read_b128 v[192:195], v149 offset:3072
	s_add_u32 s48, s48, 0x100000
	s_addc_u32 s49, s49, 0
	s_mov_b32 m0, s58
	v_lshl_add_u64 v[236:237], s[48:49], 0, v[130:131]
	ds_read_b128 v[198:201], v161 offset:32768
	ds_read_b128 v[202:205], v161 offset:33792
	ds_read_b128 v[206:209], v161 offset:34816
	ds_read_b128 v[210:213], v161 offset:35840
	ds_read_b128 v[214:217], v161 offset:36864
	ds_read_b128 v[218:221], v161 offset:37888
	ds_read_b128 v[222:225], v161 offset:38912
	ds_read_b128 v[226:229], v161 offset:39936
	global_load_lds_dwordx4 v[236:237], off
	v_lshl_add_u64 v[236:237], s[48:49], 0, v[134:135]
	s_mov_b32 m0, s59
	s_nop 0
	global_load_lds_dwordx4 v[236:237], off
	s_waitcnt vmcnt(8)
	s_waitcnt lgkmcnt(0)
	s_setprio 0
	s_barrier
	v_mfma_f32_16x16x32_bf16 v[126:129], v[152:155], v[198:201], v[126:129]
	v_mfma_f32_16x16x32_bf16 v[122:125], v[172:175], v[198:201], v[122:125]
	v_mfma_f32_16x16x32_bf16 v[110:113], v[152:155], v[206:209], v[110:113]
	v_mfma_f32_16x16x32_bf16 v[106:109], v[172:175], v[206:209], v[106:109]
	v_mfma_f32_16x16x32_bf16 v[94:97], v[152:155], v[214:217], v[94:97]
	v_mfma_f32_16x16x32_bf16 v[90:93], v[172:175], v[214:217], v[90:93]
	v_mfma_f32_16x16x32_bf16 v[78:81], v[152:155], v[222:225], v[78:81]
	v_mfma_f32_16x16x32_bf16 v[74:77], v[172:175], v[222:225], v[74:77]
	v_mfma_f32_16x16x32_bf16 v[126:129], v[168:171], v[202:205], v[126:129]
	v_mfma_f32_16x16x32_bf16 v[122:125], v[176:179], v[202:205], v[122:125]
	v_mfma_f32_16x16x32_bf16 v[110:113], v[168:171], v[210:213], v[110:113]
	v_mfma_f32_16x16x32_bf16 v[106:109], v[176:179], v[210:213], v[106:109]
	v_mfma_f32_16x16x32_bf16 v[94:97], v[168:171], v[218:221], v[94:97]
	v_mfma_f32_16x16x32_bf16 v[90:93], v[176:179], v[218:221], v[90:93]
	v_mfma_f32_16x16x32_bf16 v[78:81], v[168:171], v[226:229], v[78:81]
	v_mfma_f32_16x16x32_bf16 v[74:77], v[176:179], v[226:229], v[74:77]
	s_setprio 0
	s_setprio 0
	v_mfma_f32_16x16x32_bf16 v[118:121], v[180:183], v[198:201], v[118:121]
	v_mfma_f32_16x16x32_bf16 v[114:117], v[188:191], v[198:201], v[114:117]
	v_mfma_f32_16x16x32_bf16 v[102:105], v[180:183], v[206:209], v[102:105]
	v_mfma_f32_16x16x32_bf16 v[98:101], v[188:191], v[206:209], v[98:101]
	v_mfma_f32_16x16x32_bf16 v[86:89], v[180:183], v[214:217], v[86:89]
	v_mfma_f32_16x16x32_bf16 v[82:85], v[188:191], v[214:217], v[82:85]
	v_mfma_f32_16x16x32_bf16 v[70:73], v[180:183], v[222:225], v[70:73]
	v_mfma_f32_16x16x32_bf16 v[66:69], v[188:191], v[222:225], v[66:69]
	v_mfma_f32_16x16x32_bf16 v[118:121], v[184:187], v[202:205], v[118:121]
	v_mfma_f32_16x16x32_bf16 v[114:117], v[192:195], v[202:205], v[114:117]
	v_mfma_f32_16x16x32_bf16 v[102:105], v[184:187], v[210:213], v[102:105]
	v_mfma_f32_16x16x32_bf16 v[98:101], v[192:195], v[210:213], v[98:101]
	v_mfma_f32_16x16x32_bf16 v[86:89], v[184:187], v[218:221], v[86:89]
	v_mfma_f32_16x16x32_bf16 v[82:85], v[192:195], v[218:221], v[82:85]
	v_mfma_f32_16x16x32_bf16 v[70:73], v[184:187], v[226:229], v[70:73]
	v_mfma_f32_16x16x32_bf16 v[66:69], v[192:195], v[226:229], v[66:69]
	s_setprio 1
	s_barrier
; #define PG8_STAGE(bufoff, gbase, voff) do { _Pragma("unroll") for (int _i = 0; _i < 2; ++_i) \
;         __builtin_amdgcn_global_load_lds((const unsigned*)((const char*)(gbase) + (voff)[_i]), (PG8_LAS unsigned*)(lds + (bufoff) + ldsw + _i * 8192), 16, 0, 0); } while (0)
; #define PG8_LDA(dst, b, h) do { _Pragma("unroll") for (int m = 0; m < 4; ++m) _Pragma("unroll") for (int k = 0; k < 2; ++k) dst[m][k] = *(const PG8_LAS bf16x8*)(lds + PG8_SA(b, h) + aoff + m * 2048 + k * 1024); } while (0)
; #define PG8_MMA(ai, bj, At, Bt) do { __builtin_amdgcn_s_setprio(1); _Pragma("unroll") for (int m = 0; m < 4; ++m) _Pragma("unroll") for (int n = 0; n < 2; ++n) _Pragma("unroll") for (int k = 0; k < 2; ++k) \
;         acc[ai][bj][m][n] = __builtin_amdgcn_mfma_f32_16x16x32_bf16(Bt[n][k], At[m][k], acc[ai][bj][m][n], 0, 0, 0); __builtin_amdgcn_s_setprio(0); } while (0)
; #define PG8_WAIT_V(n) asm volatile("s_waitcnt vmcnt(" #n ")" ::: "memory")
; #define PG8_WAIT_L(n) asm volatile("s_waitcnt lgkmcnt(" #n ")" ::: "memory")
; #define PG8_BAR __builtin_amdgcn_s_barrier()
; #define PG8_SCHED __builtin_amdgcn_sched_barrier(0)
; template <class Epi, class Sched, bool ALIGN_EPI = false, bool SP2 = false>
; __device__ __forceinline__ void gemm_phase(PG8_LAS unsigned char* lds, const Gemm g, const Sched& S, const Epi& E) {
;     ...
;             PG8_LDA(At, 1, 1); PG8_STAGE(PG8_SB(1, 0), b3, voffB); PG8_STAGE(PG8_SB(1, 1), b3 + hstep, voffB); PG8_STAGE(PG8_SA(1, 0), a3, voffA);
;             PG8_WAIT_V(8); PG8_WAIT_L(0); PG8_BAR; PG8_MMA(1, 0, At, B0); PG8_MMA(1, 1, At, B1); PG8_BAR; PG8_SCHED;
;     ...
;         if constexpr (ALIGN_EPI) { if (wr == 0) PG8_BAR; }
	s_add_i32 s48, s81, s55
	v_lshl_add_u64 v[156:157], v[156:157], 0, s[10:11]
	s_mov_b32 m0, s48
	ds_read_b128 v[198:201], v161 offset:49152
	ds_read_b128 v[202:205], v161 offset:50176
	ds_read_b128 v[206:209], v161 offset:51200
	ds_read_b128 v[210:213], v161 offset:52224
	ds_read_b128 v[214:217], v161 offset:53248
	ds_read_b128 v[218:221], v161 offset:54272
	ds_read_b128 v[222:225], v161 offset:55296
	ds_read_b128 v[226:229], v161 offset:56320
	global_load_lds_dwordx4 v[156:157], off
	s_add_i32 m0, s48, 0x2000
	s_add_u32 s46, s46, 0x100080
	v_lshl_add_u64 v[156:157], v[230:231], 0, s[10:11]
	s_addc_u32 s47, s47, 0
	s_add_i32 s48, s82, s55
	global_load_lds_dwordx4 v[156:157], off
	v_lshl_add_u64 v[156:157], s[46:47], 0, v[132:133]
	s_mov_b32 m0, s48
	s_nop 0
	global_load_lds_dwordx4 v[156:157], off
	v_lshl_add_u64 v[156:157], s[46:47], 0, v[136:137]
	s_add_i32 m0, s48, 0x2000
	s_nop 0
	global_load_lds_dwordx4 v[156:157], off
	v_lshl_add_u64 v[156:157], v[232:233], 0, s[10:11]
	s_mov_b32 m0, s70
	s_nop 0
	global_load_lds_dwordx4 v[156:157], off
	v_lshl_add_u64 v[156:157], v[234:235], 0, s[10:11]
	s_mov_b32 m0, s71
	s_nop 0
	global_load_lds_dwordx4 v[156:157], off
	s_waitcnt vmcnt(8)
	s_waitcnt lgkmcnt(0)
	s_setprio 0
	s_barrier
	v_mfma_f32_16x16x32_bf16 v[62:65], v[152:155], v[198:201], v[62:65]
	v_mfma_f32_16x16x32_bf16 v[58:61], v[172:175], v[198:201], v[58:61]
	v_mfma_f32_16x16x32_bf16 v[46:49], v[152:155], v[206:209], v[46:49]
	v_mfma_f32_16x16x32_bf16 v[42:45], v[172:175], v[206:209], v[42:45]
	v_mfma_f32_16x16x32_bf16 v[30:33], v[152:155], v[214:217], v[30:33]
	v_mfma_f32_16x16x32_bf16 v[26:29], v[172:175], v[214:217], v[26:29]
	v_mfma_f32_16x16x32_bf16 v[14:17], v[152:155], v[222:225], v[14:17]
	v_mfma_f32_16x16x32_bf16 v[10:13], v[172:175], v[222:225], v[10:13]
	v_mfma_f32_16x16x32_bf16 v[62:65], v[168:171], v[202:205], v[62:65]
	v_mfma_f32_16x16x32_bf16 v[58:61], v[176:179], v[202:205], v[58:61]
	v_mfma_f32_16x16x32_bf16 v[46:49], v[168:171], v[210:213], v[46:49]
	v_mfma_f32_16x16x32_bf16 v[42:45], v[176:179], v[210:213], v[42:45]
	v_mfma_f32_16x16x32_bf16 v[30:33], v[168:171], v[218:221], v[30:33]
	v_mfma_f32_16x16x32_bf16 v[26:29], v[176:179], v[218:221], v[26:29]
	v_mfma_f32_16x16x32_bf16 v[14:17], v[168:171], v[226:229], v[14:17]
	v_mfma_f32_16x16x32_bf16 v[10:13], v[176:179], v[226:229], v[10:13]
	s_setprio 0
	s_setprio 0
	v_mfma_f32_16x16x32_bf16 v[54:57], v[180:183], v[198:201], v[54:57]
	v_mfma_f32_16x16x32_bf16 v[50:53], v[188:191], v[198:201], v[50:53]
	v_mfma_f32_16x16x32_bf16 v[38:41], v[180:183], v[206:209], v[38:41]
	v_mfma_f32_16x16x32_bf16 v[34:37], v[188:191], v[206:209], v[34:37]
	v_mfma_f32_16x16x32_bf16 v[22:25], v[180:183], v[214:217], v[22:25]
	v_mfma_f32_16x16x32_bf16 v[18:21], v[188:191], v[214:217], v[18:21]
	v_mfma_f32_16x16x32_bf16 v[6:9], v[180:183], v[222:225], v[6:9]
	v_mfma_f32_16x16x32_bf16 v[2:5], v[188:191], v[222:225], v[2:5]
	v_mfma_f32_16x16x32_bf16 v[54:57], v[184:187], v[202:205], v[54:57]
	v_mfma_f32_16x16x32_bf16 v[50:53], v[192:195], v[202:205], v[50:53]
	v_mfma_f32_16x16x32_bf16 v[38:41], v[184:187], v[210:213], v[38:41]
	v_mfma_f32_16x16x32_bf16 v[34:37], v[192:195], v[210:213], v[34:37]
	v_mfma_f32_16x16x32_bf16 v[22:25], v[184:187], v[218:221], v[22:25]
	v_mfma_f32_16x16x32_bf16 v[18:21], v[192:195], v[218:221], v[18:21]
	v_mfma_f32_16x16x32_bf16 v[6:9], v[184:187], v[226:229], v[6:9]
	v_mfma_f32_16x16x32_bf16 v[2:5], v[192:195], v[226:229], v[2:5]
	s_setprio 1
	s_barrier
	s_add_i32 s80, s80, 2
	s_add_u32 s44, s44, 0x100
	s_addc_u32 s45, s45, 0
	s_add_u32 s78, s78, 0x100
	s_addc_u32 s79, s79, 0
	s_cmp_gt_u32 s80, 61
	s_cbranch_scc0 .LBB0_217
	s_and_b64 vcc, exec, s[12:13]
	s_cbranch_vccz .LBB0_220
	s_barrier

; #define PG8_STAGE(bufoff, gbase, voff) do { _Pragma("unroll") for (int _i = 0; _i < 2; ++_i) \
;         __builtin_amdgcn_global_load_lds((const unsigned*)((const char*)(gbase) + (voff)[_i]), (PG8_LAS unsigned*)(lds + (bufoff) + ldsw + _i * 8192), 16, 0, 0); } while (0)
; #define PG8_LDA(dst, b, h) do { _Pragma("unroll") for (int m = 0; m < 4; ++m) _Pragma("unroll") for (int k = 0; k < 2; ++k) dst[m][k] = *(const PG8_LAS bf16x8*)(lds + PG8_SA(b, h) + aoff + m * 2048 + k * 1024); } while (0)
; #define PG8_LDB(dst, b, h) do { _Pragma("unroll") for (int n = 0; n < 2; ++n) _Pragma("unroll") for (int k = 0; k < 2; ++k) dst[n][k] = *(const PG8_LAS bf16x8*)(lds + PG8_SB(b, h) + boff + n * 2048 + k * 1024); } while (0)
; #define PG8_MMA(ai, bj, At, Bt) do { __builtin_amdgcn_s_setprio(1); _Pragma("unroll") for (int m = 0; m < 4; ++m) _Pragma("unroll") for (int n = 0; n < 2; ++n) _Pragma("unroll") for (int k = 0; k < 2; ++k) \
;         acc[ai][bj][m][n] = __builtin_amdgcn_mfma_f32_16x16x32_bf16(Bt[n][k], At[m][k], acc[ai][bj][m][n], 0, 0, 0); __builtin_amdgcn_s_setprio(0); } while (0)
; #define PG8_WAIT_V(n) asm volatile("s_waitcnt vmcnt(" #n ")" ::: "memory")
; template <class Epi, class Sched, bool ALIGN_EPI = false, bool SP2 = false>
; __device__ __forceinline__ void gemm_phase(PG8_LAS unsigned char* lds, const Gemm g, const Sched& S, const Epi& E) {
;     ...
;             PG8_LDB(B0, 0, 0); PG8_LDB(B1, 0, 1); PG8_SCHED; PG8_LDA(At, 0, 0); PG8_STAGE(PG8_SA(1, 1), a1 + hstep, voffA);
;             PG8_WAIT_V(8); PG8_WAIT_L(0); PG8_BAR; PG8_MMA(0, 0, At, B0); PG8_MMA(0, 1, At, B1); PG8_BAR; PG8_SCHED;
;             PG8_LDA(At, 0, 1); PG8_STAGE(PG8_SB(0, 0), b2, voffB); PG8_STAGE(PG8_SB(0, 1), b2 + hstep, voffB); PG8_STAGE(PG8_SA(0, 0), a2, voffA);
;             PG8_WAIT_V(8); PG8_WAIT_L(0); PG8_BAR; PG8_MMA(1, 0, At, B0); PG8_MMA(1, 1, At, B1); PG8_BAR; PG8_SCHED;
;             PG8_LDB(B0, 1, 0); PG8_LDB(B1, 1, 1); PG8_SCHED; PG8_LDA(At, 1, 0); PG8_STAGE(PG8_SA(0, 1), a2 + hstep, voffA);
;             PG8_WAIT_V(8); PG8_WAIT_L(0); PG8_BAR; PG8_MMA(0, 0, At, B0); PG8_MMA(0, 1, At, B1); PG8_BAR; PG8_SCHED;
;             PG8_LDA(At, 1, 1); PG8_STAGE(PG8_SB(1, 0), b3, voffB); PG8_STAGE(PG8_SB(1, 1), b3 + hstep, voffB); PG8_STAGE(PG8_SA(1, 0), a3, voffA);
;             PG8_WAIT_V(8); PG8_WAIT_L(0); PG8_BAR; PG8_MMA(1, 0, At, B0); PG8_MMA(1, 1, At, B1); PG8_BAR; PG8_SCHED;
.LBB0_710:
	ds_read_b128 v[146:149], v160
	ds_read_b128 v[164:167], v160 offset:1024
	ds_read_b128 v[168:171], v160 offset:2048
	ds_read_b128 v[172:175], v160 offset:3072
	ds_read_b128 v[176:179], v161
	ds_read_b128 v[180:183], v161 offset:1024
	ds_read_b128 v[184:187], v161 offset:2048
	ds_read_b128 v[188:191], v161 offset:3072
	s_add_u32 s50, s48, 0xfff00080
	s_addc_u32 s51, s49, -1
	s_cmp_eq_u32 s76, 60
	s_cselect_b32 s53, s43, s51
	s_cselect_b32 s52, s72, s50
	s_cselect_b32 s51, s41, s75
	s_cselect_b32 s50, s73, s74
	v_lshl_add_u64 v[226:227], s[48:49], 0, v[138:139]
	s_add_i32 m0, s9, 0xc000
	ds_read_b128 v[192:195], v162
	ds_read_b128 v[198:201], v162 offset:1024
	ds_read_b128 v[202:205], v162 offset:2048
	ds_read_b128 v[206:209], v162 offset:3072
	ds_read_b128 v[210:213], v162 offset:4096
	ds_read_b128 v[214:217], v162 offset:5120
	ds_read_b128 v[218:221], v162 offset:6144
	ds_read_b128 v[222:225], v162 offset:7168
	global_load_lds_dwordx4 v[226:227], off
	v_lshl_add_u64 v[226:227], s[48:49], 0, v[140:141]
	s_add_i32 m0, s9, 0xe000
	s_nop 0
	global_load_lds_dwordx4 v[226:227], off
	s_waitcnt vmcnt(8)
	s_waitcnt lgkmcnt(0)
	s_setprio 0
	s_barrier
	v_mfma_f32_16x16x32_bf16 v[126:129], v[146:149], v[192:195], v[126:129]
	v_mfma_f32_16x16x32_bf16 v[122:125], v[168:171], v[192:195], v[122:125]
	v_mfma_f32_16x16x32_bf16 v[110:113], v[146:149], v[202:205], v[110:113]
	v_mfma_f32_16x16x32_bf16 v[106:109], v[168:171], v[202:205], v[106:109]
	v_mfma_f32_16x16x32_bf16 v[94:97], v[146:149], v[210:213], v[94:97]
	v_mfma_f32_16x16x32_bf16 v[90:93], v[168:171], v[210:213], v[90:93]
	v_mfma_f32_16x16x32_bf16 v[78:81], v[146:149], v[218:221], v[78:81]
	v_mfma_f32_16x16x32_bf16 v[74:77], v[168:171], v[218:221], v[74:77]
	v_mfma_f32_16x16x32_bf16 v[126:129], v[164:167], v[198:201], v[126:129]
	v_mfma_f32_16x16x32_bf16 v[122:125], v[172:175], v[198:201], v[122:125]
	v_mfma_f32_16x16x32_bf16 v[110:113], v[164:167], v[206:209], v[110:113]
	v_mfma_f32_16x16x32_bf16 v[106:109], v[172:175], v[206:209], v[106:109]
	v_mfma_f32_16x16x32_bf16 v[94:97], v[164:167], v[214:217], v[94:97]
	v_mfma_f32_16x16x32_bf16 v[90:93], v[172:175], v[214:217], v[90:93]
	v_mfma_f32_16x16x32_bf16 v[78:81], v[164:167], v[222:225], v[78:81]
	v_mfma_f32_16x16x32_bf16 v[74:77], v[172:175], v[222:225], v[74:77]
	s_setprio 0
	s_setprio 0
	v_mfma_f32_16x16x32_bf16 v[118:121], v[176:179], v[192:195], v[118:121]
	v_mfma_f32_16x16x32_bf16 v[114:117], v[184:187], v[192:195], v[114:117]
	v_mfma_f32_16x16x32_bf16 v[102:105], v[176:179], v[202:205], v[102:105]
	v_mfma_f32_16x16x32_bf16 v[98:101], v[184:187], v[202:205], v[98:101]
	v_mfma_f32_16x16x32_bf16 v[86:89], v[176:179], v[210:213], v[86:89]
	v_mfma_f32_16x16x32_bf16 v[82:85], v[184:187], v[210:213], v[82:85]
	v_mfma_f32_16x16x32_bf16 v[70:73], v[176:179], v[218:221], v[70:73]
	v_mfma_f32_16x16x32_bf16 v[66:69], v[184:187], v[218:221], v[66:69]
	v_mfma_f32_16x16x32_bf16 v[118:121], v[180:183], v[198:201], v[118:121]
	v_mfma_f32_16x16x32_bf16 v[114:117], v[188:191], v[198:201], v[114:117]
	v_mfma_f32_16x16x32_bf16 v[102:105], v[180:183], v[206:209], v[102:105]
	v_mfma_f32_16x16x32_bf16 v[98:101], v[188:191], v[206:209], v[98:101]
	v_mfma_f32_16x16x32_bf16 v[86:89], v[180:183], v[214:217], v[86:89]
	v_mfma_f32_16x16x32_bf16 v[82:85], v[188:191], v[214:217], v[82:85]
	v_mfma_f32_16x16x32_bf16 v[70:73], v[180:183], v[222:225], v[70:73]
	v_mfma_f32_16x16x32_bf16 v[66:69], v[188:191], v[222:225], v[66:69]
	s_setprio 1
	s_barrier
	s_add_i32 s77, s69, s56
	v_lshl_add_u64 v[226:227], s[50:51], 0, v[132:133]
	s_mov_b32 m0, s77
	ds_read_b128 v[192:195], v162 offset:16384
	ds_read_b128 v[198:201], v162 offset:17408
	ds_read_b128 v[202:205], v162 offset:18432
	ds_read_b128 v[206:209], v162 offset:19456
	ds_read_b128 v[210:213], v162 offset:20480
	ds_read_b128 v[214:217], v162 offset:21504
	ds_read_b128 v[218:221], v162 offset:22528
	ds_read_b128 v[222:225], v162 offset:23552
	global_load_lds_dwordx4 v[226:227], off
	s_add_i32 m0, s77, 0x2000
	s_add_u32 s78, s50, 0x100000
	v_lshl_add_u64 v[228:229], s[50:51], 0, v[136:137]
	s_addc_u32 s79, s51, 0
	s_add_i32 s77, s70, s56
	global_load_lds_dwordx4 v[228:229], off
	v_lshl_add_u64 v[230:231], s[78:79], 0, v[132:133]
	s_mov_b32 m0, s77
	v_lshl_add_u64 v[232:233], s[52:53], 0, v[134:135]
	global_load_lds_dwordx4 v[230:231], off
	v_lshl_add_u64 v[230:231], s[78:79], 0, v[136:137]
	s_add_i32 m0, s77, 0x2000
	s_nop 0
	global_load_lds_dwordx4 v[230:231], off
	v_lshl_add_u64 v[230:231], s[52:53], 0, v[130:131]
	s_mov_b32 m0, s9
	s_nop 0
	global_load_lds_dwordx4 v[230:231], off
	s_mov_b32 m0, s57
	s_nop 0
	global_load_lds_dwordx4 v[232:233], off
	s_waitcnt vmcnt(8)
	s_waitcnt lgkmcnt(0)
	s_setprio 0
	s_barrier
; #define PG8_STAGE(bufoff, gbase, voff) do { _Pragma("unroll") for (int _i = 0; _i < 2; ++_i) \
;         __builtin_amdgcn_global_load_lds((const unsigned*)((const char*)(gbase) + (voff)[_i]), (PG8_LAS unsigned*)(lds + (bufoff) + ldsw + _i * 8192), 16, 0, 0); } while (0)
; #define PG8_LDA(dst, b, h) do { _Pragma("unroll") for (int m = 0; m < 4; ++m) _Pragma("unroll") for (int k = 0; k < 2; ++k) dst[m][k] = *(const PG8_LAS bf16x8*)(lds + PG8_SA(b, h) + aoff + m * 2048 + k * 1024); } while (0)
; #define PG8_LDB(dst, b, h) do { _Pragma("unroll") for (int n = 0; n < 2; ++n) _Pragma("unroll") for (int k = 0; k < 2; ++k) dst[n][k] = *(const PG8_LAS bf16x8*)(lds + PG8_SB(b, h) + boff + n * 2048 + k * 1024); } while (0)
; #define PG8_MMA(ai, bj, At, Bt) do { __builtin_amdgcn_s_setprio(1); _Pragma("unroll") for (int m = 0; m < 4; ++m) _Pragma("unroll") for (int n = 0; n < 2; ++n) _Pragma("unroll") for (int k = 0; k < 2; ++k) \
;         acc[ai][bj][m][n] = __builtin_amdgcn_mfma_f32_16x16x32_bf16(Bt[n][k], At[m][k], acc[ai][bj][m][n], 0, 0, 0); __builtin_amdgcn_s_setprio(0); } while (0)
; #define PG8_WAIT_V(n) asm volatile("s_waitcnt vmcnt(" #n ")" ::: "memory")
; template <class Epi, class Sched, bool ALIGN_EPI = false, bool SP2 = false>
; __device__ __forceinline__ void gemm_phase(PG8_LAS unsigned char* lds, const Gemm g, const Sched& S, const Epi& E) {
;     ...
;             PG8_LDB(B0, 0, 0); PG8_LDB(B1, 0, 1); PG8_SCHED; PG8_LDA(At, 0, 0); PG8_STAGE(PG8_SA(1, 1), a1 + hstep, voffA);
;             PG8_WAIT_V(8); PG8_WAIT_L(0); PG8_BAR; PG8_MMA(0, 0, At, B0); PG8_MMA(0, 1, At, B1); PG8_BAR; PG8_SCHED;
;             PG8_LDA(At, 0, 1); PG8_STAGE(PG8_SB(0, 0), b2, voffB); PG8_STAGE(PG8_SB(0, 1), b2 + hstep, voffB); PG8_STAGE(PG8_SA(0, 0), a2, voffA);
;             PG8_WAIT_V(8); PG8_WAIT_L(0); PG8_BAR; PG8_MMA(1, 0, At, B0); PG8_MMA(1, 1, At, B1); PG8_BAR; PG8_SCHED;
;             PG8_LDB(B0, 1, 0); PG8_LDB(B1, 1, 1); PG8_SCHED; PG8_LDA(At, 1, 0); PG8_STAGE(PG8_SA(0, 1), a2 + hstep, voffA);
;             PG8_WAIT_V(8); PG8_WAIT_L(0); PG8_BAR; PG8_MMA(0, 0, At, B0); PG8_MMA(0, 1, At, B1); PG8_BAR; PG8_SCHED;
;             PG8_LDA(At, 1, 1); PG8_STAGE(PG8_SB(1, 0), b3, voffB); PG8_STAGE(PG8_SB(1, 1), b3 + hstep, voffB); PG8_STAGE(PG8_SA(1, 0), a3, voffA);
;             PG8_WAIT_V(8); PG8_WAIT_L(0); PG8_BAR; PG8_MMA(1, 0, At, B0); PG8_MMA(1, 1, At, B1); PG8_BAR; PG8_SCHED;
	v_mfma_f32_16x16x32_bf16 v[62:65], v[146:149], v[192:195], v[62:65]
	v_mfma_f32_16x16x32_bf16 v[58:61], v[168:171], v[192:195], v[58:61]
	v_mfma_f32_16x16x32_bf16 v[46:49], v[146:149], v[202:205], v[46:49]
	v_mfma_f32_16x16x32_bf16 v[42:45], v[168:171], v[202:205], v[42:45]
	v_mfma_f32_16x16x32_bf16 v[30:33], v[146:149], v[210:213], v[30:33]
	v_mfma_f32_16x16x32_bf16 v[26:29], v[168:171], v[210:213], v[26:29]
	v_mfma_f32_16x16x32_bf16 v[14:17], v[146:149], v[218:221], v[14:17]
	v_mfma_f32_16x16x32_bf16 v[10:13], v[168:171], v[218:221], v[10:13]
	v_mfma_f32_16x16x32_bf16 v[62:65], v[164:167], v[198:201], v[62:65]
	v_mfma_f32_16x16x32_bf16 v[58:61], v[172:175], v[198:201], v[58:61]
	v_mfma_f32_16x16x32_bf16 v[46:49], v[164:167], v[206:209], v[46:49]
	v_mfma_f32_16x16x32_bf16 v[42:45], v[172:175], v[206:209], v[42:45]
	v_mfma_f32_16x16x32_bf16 v[30:33], v[164:167], v[214:217], v[30:33]
	v_mfma_f32_16x16x32_bf16 v[26:29], v[172:175], v[214:217], v[26:29]
	v_mfma_f32_16x16x32_bf16 v[14:17], v[164:167], v[222:225], v[14:17]
	v_mfma_f32_16x16x32_bf16 v[10:13], v[172:175], v[222:225], v[10:13]
	s_setprio 0
	s_setprio 0
	v_mfma_f32_16x16x32_bf16 v[54:57], v[176:179], v[192:195], v[54:57]
	v_mfma_f32_16x16x32_bf16 v[50:53], v[184:187], v[192:195], v[50:53]
	v_mfma_f32_16x16x32_bf16 v[38:41], v[176:179], v[202:205], v[38:41]
	v_mfma_f32_16x16x32_bf16 v[34:37], v[184:187], v[202:205], v[34:37]
	v_mfma_f32_16x16x32_bf16 v[22:25], v[176:179], v[210:213], v[22:25]
	v_mfma_f32_16x16x32_bf16 v[18:21], v[184:187], v[210:213], v[18:21]
	v_mfma_f32_16x16x32_bf16 v[6:9], v[176:179], v[218:221], v[6:9]
	v_mfma_f32_16x16x32_bf16 v[2:5], v[184:187], v[218:221], v[2:5]
	v_mfma_f32_16x16x32_bf16 v[54:57], v[180:183], v[198:201], v[54:57]
	v_mfma_f32_16x16x32_bf16 v[50:53], v[188:191], v[198:201], v[50:53]
	v_mfma_f32_16x16x32_bf16 v[38:41], v[180:183], v[206:209], v[38:41]
	v_mfma_f32_16x16x32_bf16 v[34:37], v[188:191], v[206:209], v[34:37]
	v_mfma_f32_16x16x32_bf16 v[22:25], v[180:183], v[214:217], v[22:25]
	v_mfma_f32_16x16x32_bf16 v[18:21], v[188:191], v[214:217], v[18:21]
	v_mfma_f32_16x16x32_bf16 v[6:9], v[180:183], v[222:225], v[6:9]
	v_mfma_f32_16x16x32_bf16 v[2:5], v[188:191], v[222:225], v[2:5]
	s_setprio 1
	s_barrier
	s_add_i32 s77, 0, 0x18000
	s_add_i32 s78, 0, 0x1c000
	v_add_u32_e32 v172, s77, v151
	v_add_u32_e32 v188, s78, v151
	ds_read_b128 v[146:149], v172
	ds_read_b128 v[164:167], v172 offset:1024
	ds_read_b128 v[168:171], v172 offset:2048
	ds_read_b128 v[172:175], v172 offset:3072
	ds_read_b128 v[176:179], v188
	ds_read_b128 v[180:183], v188 offset:1024
	ds_read_b128 v[184:187], v188 offset:2048
	ds_read_b128 v[188:191], v188 offset:3072
	s_add_u32 s52, s52, 0x100000
	s_addc_u32 s53, s53, 0
	s_mov_b32 m0, s58
	v_lshl_add_u64 v[234:235], s[52:53], 0, v[130:131]
	ds_read_b128 v[192:195], v162 offset:32768
	ds_read_b128 v[198:201], v162 offset:33792
	ds_read_b128 v[202:205], v162 offset:34816
	ds_read_b128 v[206:209], v162 offset:35840
	ds_read_b128 v[210:213], v162 offset:36864
	ds_read_b128 v[214:217], v162 offset:37888
	ds_read_b128 v[218:221], v162 offset:38912
	ds_read_b128 v[222:225], v162 offset:39936
	global_load_lds_dwordx4 v[234:235], off
	v_lshl_add_u64 v[234:235], s[52:53], 0, v[134:135]
	s_mov_b32 m0, s59
	s_nop 0
	global_load_lds_dwordx4 v[234:235], off
	s_waitcnt vmcnt(8)
	s_waitcnt lgkmcnt(0)
	s_setprio 0
	s_barrier
	v_mfma_f32_16x16x32_bf16 v[126:129], v[146:149], v[192:195], v[126:129]
	v_mfma_f32_16x16x32_bf16 v[122:125], v[168:171], v[192:195], v[122:125]
	v_mfma_f32_16x16x32_bf16 v[110:113], v[146:149], v[202:205], v[110:113]
	v_mfma_f32_16x16x32_bf16 v[106:109], v[168:171], v[202:205], v[106:109]
	v_mfma_f32_16x16x32_bf16 v[94:97], v[146:149], v[210:213], v[94:97]
	v_mfma_f32_16x16x32_bf16 v[90:93], v[168:171], v[210:213], v[90:93]
	v_mfma_f32_16x16x32_bf16 v[78:81], v[146:149], v[218:221], v[78:81]
	v_mfma_f32_16x16x32_bf16 v[74:77], v[168:171], v[218:221], v[74:77]
	v_mfma_f32_16x16x32_bf16 v[126:129], v[164:167], v[198:201], v[126:129]
	v_mfma_f32_16x16x32_bf16 v[122:125], v[172:175], v[198:201], v[122:125]
	v_mfma_f32_16x16x32_bf16 v[110:113], v[164:167], v[206:209], v[110:113]
	v_mfma_f32_16x16x32_bf16 v[106:109], v[172:175], v[206:209], v[106:109]
	v_mfma_f32_16x16x32_bf16 v[94:97], v[164:167], v[214:217], v[94:97]
	v_mfma_f32_16x16x32_bf16 v[90:93], v[172:175], v[214:217], v[90:93]
	v_mfma_f32_16x16x32_bf16 v[78:81], v[164:167], v[222:225], v[78:81]
	v_mfma_f32_16x16x32_bf16 v[74:77], v[172:175], v[222:225], v[74:77]
	s_setprio 0
	s_setprio 0
	v_mfma_f32_16x16x32_bf16 v[118:121], v[176:179], v[192:195], v[118:121]
	v_mfma_f32_16x16x32_bf16 v[114:117], v[184:187], v[192:195], v[114:117]
	v_mfma_f32_16x16x32_bf16 v[102:105], v[176:179], v[202:205], v[102:105]
	v_mfma_f32_16x16x32_bf16 v[98:101], v[184:187], v[202:205], v[98:101]
	v_mfma_f32_16x16x32_bf16 v[86:89], v[176:179], v[210:213], v[86:89]
	v_mfma_f32_16x16x32_bf16 v[82:85], v[184:187], v[210:213], v[82:85]
	v_mfma_f32_16x16x32_bf16 v[70:73], v[176:179], v[218:221], v[70:73]
	v_mfma_f32_16x16x32_bf16 v[66:69], v[184:187], v[218:221], v[66:69]
	v_mfma_f32_16x16x32_bf16 v[118:121], v[180:183], v[198:201], v[118:121]
	v_mfma_f32_16x16x32_bf16 v[114:117], v[188:191], v[198:201], v[114:117]
	v_mfma_f32_16x16x32_bf16 v[102:105], v[180:183], v[206:209], v[102:105]
	v_mfma_f32_16x16x32_bf16 v[98:101], v[188:191], v[206:209], v[98:101]
	v_mfma_f32_16x16x32_bf16 v[86:89], v[180:183], v[214:217], v[86:89]
	v_mfma_f32_16x16x32_bf16 v[82:85], v[188:191], v[214:217], v[82:85]
	v_mfma_f32_16x16x32_bf16 v[70:73], v[180:183], v[222:225], v[70:73]
	v_mfma_f32_16x16x32_bf16 v[66:69], v[188:191], v[222:225], v[66:69]
	s_setprio 1
	s_barrier
; #define PG8_STAGE(bufoff, gbase, voff) do { _Pragma("unroll") for (int _i = 0; _i < 2; ++_i) \
;         __builtin_amdgcn_global_load_lds((const unsigned*)((const char*)(gbase) + (voff)[_i]), (PG8_LAS unsigned*)(lds + (bufoff) + ldsw + _i * 8192), 16, 0, 0); } while (0)
; #define PG8_LDA(dst, b, h) do { _Pragma("unroll") for (int m = 0; m < 4; ++m) _Pragma("unroll") for (int k = 0; k < 2; ++k) dst[m][k] = *(const PG8_LAS bf16x8*)(lds + PG8_SA(b, h) + aoff + m * 2048 + k * 1024); } while (0)
; #define PG8_MMA(ai, bj, At, Bt) do { __builtin_amdgcn_s_setprio(1); _Pragma("unroll") for (int m = 0; m < 4; ++m) _Pragma("unroll") for (int n = 0; n < 2; ++n) _Pragma("unroll") for (int k = 0; k < 2; ++k) \
;         acc[ai][bj][m][n] = __builtin_amdgcn_mfma_f32_16x16x32_bf16(Bt[n][k], At[m][k], acc[ai][bj][m][n], 0, 0, 0); __builtin_amdgcn_s_setprio(0); } while (0)
; #define PG8_WAIT_V(n) asm volatile("s_waitcnt vmcnt(" #n ")" ::: "memory")
; #define PG8_WAIT_L(n) asm volatile("s_waitcnt lgkmcnt(" #n ")" ::: "memory")
; #define PG8_BAR __builtin_amdgcn_s_barrier()
; #define PG8_SCHED __builtin_amdgcn_sched_barrier(0)
; template <class Epi, class Sched, bool ALIGN_EPI = false, bool SP2 = false>
; __device__ __forceinline__ void gemm_phase(PG8_LAS unsigned char* lds, const Gemm g, const Sched& S, const Epi& E) {
;     ...
;             PG8_LDA(At, 1, 1); PG8_STAGE(PG8_SB(1, 0), b3, voffB); PG8_STAGE(PG8_SB(1, 1), b3 + hstep, voffB); PG8_STAGE(PG8_SA(1, 0), a3, voffA);
;             PG8_WAIT_V(8); PG8_WAIT_L(0); PG8_BAR; PG8_MMA(1, 0, At, B0); PG8_MMA(1, 1, At, B1); PG8_BAR; PG8_SCHED;
;     ...
;         if constexpr (ALIGN_EPI) { if (wr == 0) PG8_BAR; }
	s_add_i32 s52, s77, s56
	v_lshl_add_u64 v[226:227], v[226:227], 0, s[36:37]
	s_mov_b32 m0, s52
	ds_read_b128 v[192:195], v162 offset:49152
	ds_read_b128 v[198:201], v162 offset:50176
	ds_read_b128 v[202:205], v162 offset:51200
	ds_read_b128 v[206:209], v162 offset:52224
	ds_read_b128 v[210:213], v162 offset:53248
	ds_read_b128 v[214:217], v162 offset:54272
	ds_read_b128 v[218:221], v162 offset:55296
	ds_read_b128 v[222:225], v162 offset:56320
	global_load_lds_dwordx4 v[226:227], off
	s_add_i32 m0, s52, 0x2000
	s_add_u32 s50, s50, 0x100080
	v_lshl_add_u64 v[226:227], v[228:229], 0, s[36:37]
	s_addc_u32 s51, s51, 0
	s_add_i32 s52, s78, s56
	global_load_lds_dwordx4 v[226:227], off
	v_lshl_add_u64 v[226:227], s[50:51], 0, v[132:133]
	s_mov_b32 m0, s52
	s_nop 0
	global_load_lds_dwordx4 v[226:227], off
	v_lshl_add_u64 v[226:227], s[50:51], 0, v[136:137]
	s_add_i32 m0, s52, 0x2000
	s_nop 0
	global_load_lds_dwordx4 v[226:227], off
	v_lshl_add_u64 v[226:227], v[230:231], 0, s[36:37]
	s_mov_b32 m0, s61
	s_nop 0
	global_load_lds_dwordx4 v[226:227], off
	v_lshl_add_u64 v[226:227], v[232:233], 0, s[36:37]
	s_mov_b32 m0, s62
	s_nop 0
	global_load_lds_dwordx4 v[226:227], off
	s_waitcnt vmcnt(8)
	s_waitcnt lgkmcnt(0)
	s_setprio 0
	s_barrier
	v_mfma_f32_16x16x32_bf16 v[62:65], v[146:149], v[192:195], v[62:65]
	v_mfma_f32_16x16x32_bf16 v[58:61], v[168:171], v[192:195], v[58:61]
	v_mfma_f32_16x16x32_bf16 v[46:49], v[146:149], v[202:205], v[46:49]
	v_mfma_f32_16x16x32_bf16 v[42:45], v[168:171], v[202:205], v[42:45]
	v_mfma_f32_16x16x32_bf16 v[30:33], v[146:149], v[210:213], v[30:33]
	v_mfma_f32_16x16x32_bf16 v[26:29], v[168:171], v[210:213], v[26:29]
	v_mfma_f32_16x16x32_bf16 v[14:17], v[146:149], v[218:221], v[14:17]
	v_mfma_f32_16x16x32_bf16 v[10:13], v[168:171], v[218:221], v[10:13]
	v_mfma_f32_16x16x32_bf16 v[62:65], v[164:167], v[198:201], v[62:65]
	v_mfma_f32_16x16x32_bf16 v[58:61], v[172:175], v[198:201], v[58:61]
	v_mfma_f32_16x16x32_bf16 v[46:49], v[164:167], v[206:209], v[46:49]
	v_mfma_f32_16x16x32_bf16 v[42:45], v[172:175], v[206:209], v[42:45]
	v_mfma_f32_16x16x32_bf16 v[30:33], v[164:167], v[214:217], v[30:33]
	v_mfma_f32_16x16x32_bf16 v[26:29], v[172:175], v[214:217], v[26:29]
	v_mfma_f32_16x16x32_bf16 v[14:17], v[164:167], v[222:225], v[14:17]
	v_mfma_f32_16x16x32_bf16 v[10:13], v[172:175], v[222:225], v[10:13]
	s_setprio 0
	s_setprio 0
	v_mfma_f32_16x16x32_bf16 v[54:57], v[176:179], v[192:195], v[54:57]
	v_mfma_f32_16x16x32_bf16 v[50:53], v[184:187], v[192:195], v[50:53]
	v_mfma_f32_16x16x32_bf16 v[38:41], v[176:179], v[202:205], v[38:41]
	v_mfma_f32_16x16x32_bf16 v[34:37], v[184:187], v[202:205], v[34:37]
	v_mfma_f32_16x16x32_bf16 v[22:25], v[176:179], v[210:213], v[22:25]
	v_mfma_f32_16x16x32_bf16 v[18:21], v[184:187], v[210:213], v[18:21]
	v_mfma_f32_16x16x32_bf16 v[6:9], v[176:179], v[218:221], v[6:9]
	v_mfma_f32_16x16x32_bf16 v[2:5], v[184:187], v[218:221], v[2:5]
	v_mfma_f32_16x16x32_bf16 v[54:57], v[180:183], v[198:201], v[54:57]
	v_mfma_f32_16x16x32_bf16 v[50:53], v[188:191], v[198:201], v[50:53]
	v_mfma_f32_16x16x32_bf16 v[38:41], v[180:183], v[206:209], v[38:41]
	v_mfma_f32_16x16x32_bf16 v[34:37], v[188:191], v[206:209], v[34:37]
	v_mfma_f32_16x16x32_bf16 v[22:25], v[180:183], v[214:217], v[22:25]
	v_mfma_f32_16x16x32_bf16 v[18:21], v[188:191], v[214:217], v[18:21]
	v_mfma_f32_16x16x32_bf16 v[6:9], v[180:183], v[222:225], v[6:9]
	v_mfma_f32_16x16x32_bf16 v[2:5], v[188:191], v[222:225], v[2:5]
	s_setprio 1
	s_barrier
	s_add_i32 s76, s76, 2
	s_add_u32 s48, s48, 0x100
	s_addc_u32 s49, s49, 0
	s_add_u32 s74, s74, 0x100
	s_addc_u32 s75, s75, 0
	s_cmp_gt_u32 s76, 61
	s_cbranch_scc0 .LBB0_710
	s_and_b64 vcc, exec, s[38:39]
	s_cbranch_vccz .LBB0_713
	s_barrier

; #define PG8_STAGE(bufoff, gbase, voff) do { _Pragma("unroll") for (int _i = 0; _i < 2; ++_i) \
;         __builtin_amdgcn_global_load_lds((const unsigned*)((const char*)(gbase) + (voff)[_i]), (PG8_LAS unsigned*)(lds + (bufoff) + ldsw + _i * 8192), 16, 0, 0); } while (0)
; #define PG8_LDA(dst, b, h) do { _Pragma("unroll") for (int m = 0; m < 4; ++m) _Pragma("unroll") for (int k = 0; k < 2; ++k) dst[m][k] = *(const PG8_LAS bf16x8*)(lds + PG8_SA(b, h) + aoff + m * 2048 + k * 1024); } while (0)
; #define PG8_LDB(dst, b, h) do { _Pragma("unroll") for (int n = 0; n < 2; ++n) _Pragma("unroll") for (int k = 0; k < 2; ++k) dst[n][k] = *(const PG8_LAS bf16x8*)(lds + PG8_SB(b, h) + boff + n * 2048 + k * 1024); } while (0)
; #define PG8_MMA(ai, bj, At, Bt) do { __builtin_amdgcn_s_setprio(1); _Pragma("unroll") for (int m = 0; m < 4; ++m) _Pragma("unroll") for (int n = 0; n < 2; ++n) _Pragma("unroll") for (int k = 0; k < 2; ++k) \
;         acc[ai][bj][m][n] = __builtin_amdgcn_mfma_f32_16x16x32_bf16(Bt[n][k], At[m][k], acc[ai][bj][m][n], 0, 0, 0); __builtin_amdgcn_s_setprio(0); } while (0)
; #define PG8_WAIT_V(n) asm volatile("s_waitcnt vmcnt(" #n ")" ::: "memory")
; template <class Epi, class Sched, bool ALIGN_EPI = false, bool SP2 = false>
; __device__ __forceinline__ void gemm_phase(PG8_LAS unsigned char* lds, const Gemm g, const Sched& S, const Epi& E) {
;     ...
;             PG8_LDB(B0, 0, 0); PG8_LDB(B1, 0, 1); PG8_SCHED; PG8_LDA(At, 0, 0); PG8_STAGE(PG8_SA(1, 1), a1 + hstep, voffA);
;             PG8_WAIT_V(8); PG8_WAIT_L(0); PG8_BAR; PG8_MMA(0, 0, At, B0); PG8_MMA(0, 1, At, B1); PG8_BAR; PG8_SCHED;
;             PG8_LDA(At, 0, 1); PG8_STAGE(PG8_SB(0, 0), b2, voffB); PG8_STAGE(PG8_SB(0, 1), b2 + hstep, voffB); PG8_STAGE(PG8_SA(0, 0), a2, voffA);
;             PG8_WAIT_V(8); PG8_WAIT_L(0); PG8_BAR; PG8_MMA(1, 0, At, B0); PG8_MMA(1, 1, At, B1); PG8_BAR; PG8_SCHED;
;             PG8_LDB(B0, 1, 0); PG8_LDB(B1, 1, 1); PG8_SCHED; PG8_LDA(At, 1, 0); PG8_STAGE(PG8_SA(0, 1), a2 + hstep, voffA);
;             PG8_WAIT_V(8); PG8_WAIT_L(0); PG8_BAR; PG8_MMA(0, 0, At, B0); PG8_MMA(0, 1, At, B1); PG8_BAR; PG8_SCHED;
;             PG8_LDA(At, 1, 1); PG8_STAGE(PG8_SB(1, 0), b3, voffB); PG8_STAGE(PG8_SB(1, 1), b3 + hstep, voffB); PG8_STAGE(PG8_SA(1, 0), a3, voffA);
;             PG8_WAIT_V(8); PG8_WAIT_L(0); PG8_BAR; PG8_MMA(1, 0, At, B0); PG8_MMA(1, 1, At, B1); PG8_BAR; PG8_SCHED;
.LBB0_881:
	ds_read_b128 v[156:159], v152
	ds_read_b128 v[160:163], v152 offset:1024
	ds_read_b128 v[164:167], v152 offset:2048
	ds_read_b128 v[168:171], v152 offset:3072
	ds_read_b128 v[172:175], v153
	ds_read_b128 v[176:179], v153 offset:1024
	ds_read_b128 v[180:183], v153 offset:2048
	ds_read_b128 v[184:187], v153 offset:3072
	s_add_u32 s46, s44, 0xfff00080
	s_addc_u32 s47, s45, -1
	s_cmp_eq_u32 s74, 60
	s_cselect_b32 s49, s37, s47
	s_cselect_b32 s48, s70, s46
	s_cselect_b32 s47, s35, s73
	s_cselect_b32 s46, s71, s72
	v_lshl_add_u64 v[146:147], s[44:45], 0, v[138:139]
	s_add_i32 m0, s43, 0xc000
	ds_read_b128 v[188:191], v154
	ds_read_b128 v[192:195], v154 offset:1024
	ds_read_b128 v[198:201], v154 offset:2048
	ds_read_b128 v[202:205], v154 offset:3072
	ds_read_b128 v[206:209], v154 offset:4096
	ds_read_b128 v[210:213], v154 offset:5120
	ds_read_b128 v[214:217], v154 offset:6144
	ds_read_b128 v[218:221], v154 offset:7168
	global_load_lds_dwordx4 v[146:147], off
	v_lshl_add_u64 v[146:147], s[44:45], 0, v[140:141]
	s_add_i32 m0, s43, 0xe000
	s_nop 0
	global_load_lds_dwordx4 v[146:147], off
	s_waitcnt vmcnt(8)
	s_waitcnt lgkmcnt(0)
	s_setprio 0
	s_barrier
	v_mfma_f32_16x16x32_bf16 v[122:125], v[156:159], v[188:191], v[122:125]
	v_mfma_f32_16x16x32_bf16 v[114:117], v[164:167], v[188:191], v[114:117]
	v_mfma_f32_16x16x32_bf16 v[106:109], v[156:159], v[198:201], v[106:109]
	v_mfma_f32_16x16x32_bf16 v[98:101], v[164:167], v[198:201], v[98:101]
	v_mfma_f32_16x16x32_bf16 v[90:93], v[156:159], v[206:209], v[90:93]
	v_mfma_f32_16x16x32_bf16 v[82:85], v[164:167], v[206:209], v[82:85]
	v_mfma_f32_16x16x32_bf16 v[74:77], v[156:159], v[214:217], v[74:77]
	v_mfma_f32_16x16x32_bf16 v[66:69], v[164:167], v[214:217], v[66:69]
	v_mfma_f32_16x16x32_bf16 v[122:125], v[160:163], v[192:195], v[122:125]
	v_mfma_f32_16x16x32_bf16 v[114:117], v[168:171], v[192:195], v[114:117]
	v_mfma_f32_16x16x32_bf16 v[106:109], v[160:163], v[202:205], v[106:109]
	v_mfma_f32_16x16x32_bf16 v[98:101], v[168:171], v[202:205], v[98:101]
	v_mfma_f32_16x16x32_bf16 v[90:93], v[160:163], v[210:213], v[90:93]
	v_mfma_f32_16x16x32_bf16 v[82:85], v[168:171], v[210:213], v[82:85]
	v_mfma_f32_16x16x32_bf16 v[74:77], v[160:163], v[218:221], v[74:77]
	v_mfma_f32_16x16x32_bf16 v[66:69], v[168:171], v[218:221], v[66:69]
	s_setprio 0
	s_setprio 0
	v_mfma_f32_16x16x32_bf16 v[126:129], v[172:175], v[188:191], v[126:129]
	v_mfma_f32_16x16x32_bf16 v[118:121], v[180:183], v[188:191], v[118:121]
	v_mfma_f32_16x16x32_bf16 v[110:113], v[172:175], v[198:201], v[110:113]
	v_mfma_f32_16x16x32_bf16 v[102:105], v[180:183], v[198:201], v[102:105]
	v_mfma_f32_16x16x32_bf16 v[94:97], v[172:175], v[206:209], v[94:97]
	v_mfma_f32_16x16x32_bf16 v[86:89], v[180:183], v[206:209], v[86:89]
	v_mfma_f32_16x16x32_bf16 v[78:81], v[172:175], v[214:217], v[78:81]
	v_mfma_f32_16x16x32_bf16 v[70:73], v[180:183], v[214:217], v[70:73]
	v_mfma_f32_16x16x32_bf16 v[126:129], v[176:179], v[192:195], v[126:129]
	v_mfma_f32_16x16x32_bf16 v[118:121], v[184:187], v[192:195], v[118:121]
	v_mfma_f32_16x16x32_bf16 v[110:113], v[176:179], v[202:205], v[110:113]
	v_mfma_f32_16x16x32_bf16 v[102:105], v[184:187], v[202:205], v[102:105]
	v_mfma_f32_16x16x32_bf16 v[94:97], v[176:179], v[210:213], v[94:97]
	v_mfma_f32_16x16x32_bf16 v[86:89], v[184:187], v[210:213], v[86:89]
	v_mfma_f32_16x16x32_bf16 v[78:81], v[176:179], v[218:221], v[78:81]
	v_mfma_f32_16x16x32_bf16 v[70:73], v[184:187], v[218:221], v[70:73]
	s_setprio 1
	s_barrier
	s_add_i32 s75, s63, s52
	v_lshl_add_u64 v[146:147], s[46:47], 0, v[134:135]
	s_mov_b32 m0, s75
	ds_read_b128 v[188:191], v154 offset:16384
	ds_read_b128 v[192:195], v154 offset:17408
	ds_read_b128 v[198:201], v154 offset:18432
	ds_read_b128 v[202:205], v154 offset:19456
	ds_read_b128 v[206:209], v154 offset:20480
	ds_read_b128 v[210:213], v154 offset:21504
	ds_read_b128 v[214:217], v154 offset:22528
	ds_read_b128 v[218:221], v154 offset:23552
	global_load_lds_dwordx4 v[146:147], off
	s_add_i32 m0, s75, 0x2000
	s_add_u32 s76, s46, 0x100000
	v_lshl_add_u64 v[222:223], s[46:47], 0, v[130:131]
	s_addc_u32 s77, s47, 0
	s_add_i32 s75, s67, s52
	global_load_lds_dwordx4 v[222:223], off
	v_lshl_add_u64 v[224:225], s[76:77], 0, v[134:135]
	s_mov_b32 m0, s75
	v_lshl_add_u64 v[226:227], s[48:49], 0, v[132:133]
	global_load_lds_dwordx4 v[224:225], off
	v_lshl_add_u64 v[224:225], s[76:77], 0, v[130:131]
	s_add_i32 m0, s75, 0x2000
	s_nop 0
	global_load_lds_dwordx4 v[224:225], off
	v_lshl_add_u64 v[224:225], s[48:49], 0, v[136:137]
	s_mov_b32 m0, s43
	s_nop 0
	global_load_lds_dwordx4 v[224:225], off
	s_mov_b32 m0, s55
	s_nop 0
	global_load_lds_dwordx4 v[226:227], off
	s_waitcnt vmcnt(8)
	s_waitcnt lgkmcnt(0)
	s_setprio 0
	s_barrier
; #define PG8_STAGE(bufoff, gbase, voff) do { _Pragma("unroll") for (int _i = 0; _i < 2; ++_i) \
;         __builtin_amdgcn_global_load_lds((const unsigned*)((const char*)(gbase) + (voff)[_i]), (PG8_LAS unsigned*)(lds + (bufoff) + ldsw + _i * 8192), 16, 0, 0); } while (0)
; #define PG8_LDA(dst, b, h) do { _Pragma("unroll") for (int m = 0; m < 4; ++m) _Pragma("unroll") for (int k = 0; k < 2; ++k) dst[m][k] = *(const PG8_LAS bf16x8*)(lds + PG8_SA(b, h) + aoff + m * 2048 + k * 1024); } while (0)
; #define PG8_LDB(dst, b, h) do { _Pragma("unroll") for (int n = 0; n < 2; ++n) _Pragma("unroll") for (int k = 0; k < 2; ++k) dst[n][k] = *(const PG8_LAS bf16x8*)(lds + PG8_SB(b, h) + boff + n * 2048 + k * 1024); } while (0)
; #define PG8_MMA(ai, bj, At, Bt) do { __builtin_amdgcn_s_setprio(1); _Pragma("unroll") for (int m = 0; m < 4; ++m) _Pragma("unroll") for (int n = 0; n < 2; ++n) _Pragma("unroll") for (int k = 0; k < 2; ++k) \
;         acc[ai][bj][m][n] = __builtin_amdgcn_mfma_f32_16x16x32_bf16(Bt[n][k], At[m][k], acc[ai][bj][m][n], 0, 0, 0); __builtin_amdgcn_s_setprio(0); } while (0)
; #define PG8_WAIT_V(n) asm volatile("s_waitcnt vmcnt(" #n ")" ::: "memory")
; template <class Epi, class Sched, bool ALIGN_EPI = false, bool SP2 = false>
; __device__ __forceinline__ void gemm_phase(PG8_LAS unsigned char* lds, const Gemm g, const Sched& S, const Epi& E) {
;     ...
;             PG8_LDB(B0, 0, 0); PG8_LDB(B1, 0, 1); PG8_SCHED; PG8_LDA(At, 0, 0); PG8_STAGE(PG8_SA(1, 1), a1 + hstep, voffA);
;             PG8_WAIT_V(8); PG8_WAIT_L(0); PG8_BAR; PG8_MMA(0, 0, At, B0); PG8_MMA(0, 1, At, B1); PG8_BAR; PG8_SCHED;
;             PG8_LDA(At, 0, 1); PG8_STAGE(PG8_SB(0, 0), b2, voffB); PG8_STAGE(PG8_SB(0, 1), b2 + hstep, voffB); PG8_STAGE(PG8_SA(0, 0), a2, voffA);
;             PG8_WAIT_V(8); PG8_WAIT_L(0); PG8_BAR; PG8_MMA(1, 0, At, B0); PG8_MMA(1, 1, At, B1); PG8_BAR; PG8_SCHED;
;             PG8_LDB(B0, 1, 0); PG8_LDB(B1, 1, 1); PG8_SCHED; PG8_LDA(At, 1, 0); PG8_STAGE(PG8_SA(0, 1), a2 + hstep, voffA);
;             PG8_WAIT_V(8); PG8_WAIT_L(0); PG8_BAR; PG8_MMA(0, 0, At, B0); PG8_MMA(0, 1, At, B1); PG8_BAR; PG8_SCHED;
;             PG8_LDA(At, 1, 1); PG8_STAGE(PG8_SB(1, 0), b3, voffB); PG8_STAGE(PG8_SB(1, 1), b3 + hstep, voffB); PG8_STAGE(PG8_SA(1, 0), a3, voffA);
;             PG8_WAIT_V(8); PG8_WAIT_L(0); PG8_BAR; PG8_MMA(1, 0, At, B0); PG8_MMA(1, 1, At, B1); PG8_BAR; PG8_SCHED;
	v_mfma_f32_16x16x32_bf16 v[58:61], v[156:159], v[188:191], v[58:61]
	v_mfma_f32_16x16x32_bf16 v[50:53], v[164:167], v[188:191], v[50:53]
	v_mfma_f32_16x16x32_bf16 v[42:45], v[156:159], v[198:201], v[42:45]
	v_mfma_f32_16x16x32_bf16 v[34:37], v[164:167], v[198:201], v[34:37]
	v_mfma_f32_16x16x32_bf16 v[26:29], v[156:159], v[206:209], v[26:29]
	v_mfma_f32_16x16x32_bf16 v[18:21], v[164:167], v[206:209], v[18:21]
	v_mfma_f32_16x16x32_bf16 v[10:13], v[156:159], v[214:217], v[10:13]
	v_mfma_f32_16x16x32_bf16 v[6:9], v[164:167], v[214:217], v[6:9]
	v_mfma_f32_16x16x32_bf16 v[58:61], v[160:163], v[192:195], v[58:61]
	v_mfma_f32_16x16x32_bf16 v[50:53], v[168:171], v[192:195], v[50:53]
	v_mfma_f32_16x16x32_bf16 v[42:45], v[160:163], v[202:205], v[42:45]
	v_mfma_f32_16x16x32_bf16 v[34:37], v[168:171], v[202:205], v[34:37]
	v_mfma_f32_16x16x32_bf16 v[26:29], v[160:163], v[210:213], v[26:29]
	v_mfma_f32_16x16x32_bf16 v[18:21], v[168:171], v[210:213], v[18:21]
	v_mfma_f32_16x16x32_bf16 v[10:13], v[160:163], v[218:221], v[10:13]
	v_mfma_f32_16x16x32_bf16 v[6:9], v[168:171], v[218:221], v[6:9]
	s_setprio 0
	s_setprio 0
	v_mfma_f32_16x16x32_bf16 v[62:65], v[172:175], v[188:191], v[62:65]
	v_mfma_f32_16x16x32_bf16 v[54:57], v[180:183], v[188:191], v[54:57]
	v_mfma_f32_16x16x32_bf16 v[46:49], v[172:175], v[198:201], v[46:49]
	v_mfma_f32_16x16x32_bf16 v[38:41], v[180:183], v[198:201], v[38:41]
	v_mfma_f32_16x16x32_bf16 v[30:33], v[172:175], v[206:209], v[30:33]
	v_mfma_f32_16x16x32_bf16 v[22:25], v[180:183], v[206:209], v[22:25]
	v_mfma_f32_16x16x32_bf16 v[14:17], v[172:175], v[214:217], v[14:17]
	v_mfma_f32_16x16x32_bf16 v[2:5], v[180:183], v[214:217], v[2:5]
	v_mfma_f32_16x16x32_bf16 v[62:65], v[176:179], v[192:195], v[62:65]
	v_mfma_f32_16x16x32_bf16 v[54:57], v[184:187], v[192:195], v[54:57]
	v_mfma_f32_16x16x32_bf16 v[46:49], v[176:179], v[202:205], v[46:49]
	v_mfma_f32_16x16x32_bf16 v[38:41], v[184:187], v[202:205], v[38:41]
	v_mfma_f32_16x16x32_bf16 v[30:33], v[176:179], v[210:213], v[30:33]
	v_mfma_f32_16x16x32_bf16 v[22:25], v[184:187], v[210:213], v[22:25]
	v_mfma_f32_16x16x32_bf16 v[14:17], v[176:179], v[218:221], v[14:17]
	v_mfma_f32_16x16x32_bf16 v[2:5], v[184:187], v[218:221], v[2:5]
	s_setprio 1
	s_barrier
	s_add_i32 s75, 0, 0x18000
	v_add_u32_e32 v155, s75, v150
	s_add_i32 s76, 0, 0x1c000
	ds_read_b128 v[156:159], v155
	ds_read_b128 v[160:163], v155 offset:1024
	ds_read_b128 v[164:167], v155 offset:2048
	ds_read_b128 v[168:171], v155 offset:3072
	v_add_u32_e32 v155, s76, v150
	ds_read_b128 v[172:175], v155
	ds_read_b128 v[176:179], v155 offset:1024
	ds_read_b128 v[180:183], v155 offset:2048
	ds_read_b128 v[184:187], v155 offset:3072
	s_add_u32 s48, s48, 0x100000
	s_addc_u32 s49, s49, 0
	s_mov_b32 m0, s56
	v_lshl_add_u64 v[228:229], s[48:49], 0, v[136:137]
	ds_read_b128 v[188:191], v154 offset:32768
	ds_read_b128 v[192:195], v154 offset:33792
	ds_read_b128 v[198:201], v154 offset:34816
	ds_read_b128 v[202:205], v154 offset:35840
	ds_read_b128 v[206:209], v154 offset:36864
	ds_read_b128 v[210:213], v154 offset:37888
	ds_read_b128 v[214:217], v154 offset:38912
	ds_read_b128 v[218:221], v154 offset:39936
	global_load_lds_dwordx4 v[228:229], off
	v_lshl_add_u64 v[228:229], s[48:49], 0, v[132:133]
	s_mov_b32 m0, s57
	s_nop 0
	global_load_lds_dwordx4 v[228:229], off
	s_waitcnt vmcnt(8)
	s_waitcnt lgkmcnt(0)
	s_setprio 0
	s_barrier
	v_mfma_f32_16x16x32_bf16 v[122:125], v[156:159], v[188:191], v[122:125]
	v_mfma_f32_16x16x32_bf16 v[114:117], v[164:167], v[188:191], v[114:117]
	v_mfma_f32_16x16x32_bf16 v[106:109], v[156:159], v[198:201], v[106:109]
	v_mfma_f32_16x16x32_bf16 v[98:101], v[164:167], v[198:201], v[98:101]
	v_mfma_f32_16x16x32_bf16 v[90:93], v[156:159], v[206:209], v[90:93]
	v_mfma_f32_16x16x32_bf16 v[82:85], v[164:167], v[206:209], v[82:85]
	v_mfma_f32_16x16x32_bf16 v[74:77], v[156:159], v[214:217], v[74:77]
	v_mfma_f32_16x16x32_bf16 v[66:69], v[164:167], v[214:217], v[66:69]
	v_mfma_f32_16x16x32_bf16 v[122:125], v[160:163], v[192:195], v[122:125]
	v_mfma_f32_16x16x32_bf16 v[114:117], v[168:171], v[192:195], v[114:117]
	v_mfma_f32_16x16x32_bf16 v[106:109], v[160:163], v[202:205], v[106:109]
	v_mfma_f32_16x16x32_bf16 v[98:101], v[168:171], v[202:205], v[98:101]
	v_mfma_f32_16x16x32_bf16 v[90:93], v[160:163], v[210:213], v[90:93]
	v_mfma_f32_16x16x32_bf16 v[82:85], v[168:171], v[210:213], v[82:85]
	v_mfma_f32_16x16x32_bf16 v[74:77], v[160:163], v[218:221], v[74:77]
	v_mfma_f32_16x16x32_bf16 v[66:69], v[168:171], v[218:221], v[66:69]
	s_setprio 0
	s_setprio 0
	v_mfma_f32_16x16x32_bf16 v[126:129], v[172:175], v[188:191], v[126:129]
	v_mfma_f32_16x16x32_bf16 v[118:121], v[180:183], v[188:191], v[118:121]
	v_mfma_f32_16x16x32_bf16 v[110:113], v[172:175], v[198:201], v[110:113]
	v_mfma_f32_16x16x32_bf16 v[102:105], v[180:183], v[198:201], v[102:105]
	v_mfma_f32_16x16x32_bf16 v[94:97], v[172:175], v[206:209], v[94:97]
	v_mfma_f32_16x16x32_bf16 v[86:89], v[180:183], v[206:209], v[86:89]
	v_mfma_f32_16x16x32_bf16 v[78:81], v[172:175], v[214:217], v[78:81]
	v_mfma_f32_16x16x32_bf16 v[70:73], v[180:183], v[214:217], v[70:73]
	v_mfma_f32_16x16x32_bf16 v[126:129], v[176:179], v[192:195], v[126:129]
	v_mfma_f32_16x16x32_bf16 v[118:121], v[184:187], v[192:195], v[118:121]
	v_mfma_f32_16x16x32_bf16 v[110:113], v[176:179], v[202:205], v[110:113]
	v_mfma_f32_16x16x32_bf16 v[102:105], v[184:187], v[202:205], v[102:105]
	v_mfma_f32_16x16x32_bf16 v[94:97], v[176:179], v[210:213], v[94:97]
	v_mfma_f32_16x16x32_bf16 v[86:89], v[184:187], v[210:213], v[86:89]
	v_mfma_f32_16x16x32_bf16 v[78:81], v[176:179], v[218:221], v[78:81]
	v_mfma_f32_16x16x32_bf16 v[70:73], v[184:187], v[218:221], v[70:73]
	s_setprio 1
	s_barrier
; #define PG8_STAGE(bufoff, gbase, voff) do { _Pragma("unroll") for (int _i = 0; _i < 2; ++_i) \
;         __builtin_amdgcn_global_load_lds((const unsigned*)((const char*)(gbase) + (voff)[_i]), (PG8_LAS unsigned*)(lds + (bufoff) + ldsw + _i * 8192), 16, 0, 0); } while (0)
; #define PG8_LDA(dst, b, h) do { _Pragma("unroll") for (int m = 0; m < 4; ++m) _Pragma("unroll") for (int k = 0; k < 2; ++k) dst[m][k] = *(const PG8_LAS bf16x8*)(lds + PG8_SA(b, h) + aoff + m * 2048 + k * 1024); } while (0)
; #define PG8_MMA(ai, bj, At, Bt) do { __builtin_amdgcn_s_setprio(1); _Pragma("unroll") for (int m = 0; m < 4; ++m) _Pragma("unroll") for (int n = 0; n < 2; ++n) _Pragma("unroll") for (int k = 0; k < 2; ++k) \
;         acc[ai][bj][m][n] = __builtin_amdgcn_mfma_f32_16x16x32_bf16(Bt[n][k], At[m][k], acc[ai][bj][m][n], 0, 0, 0); __builtin_amdgcn_s_setprio(0); } while (0)
; #define PG8_WAIT_V(n) asm volatile("s_waitcnt vmcnt(" #n ")" ::: "memory")
; #define PG8_WAIT_L(n) asm volatile("s_waitcnt lgkmcnt(" #n ")" ::: "memory")
; #define PG8_BAR __builtin_amdgcn_s_barrier()
; #define PG8_SCHED __builtin_amdgcn_sched_barrier(0)
; template <class Epi, class Sched, bool ALIGN_EPI = false, bool SP2 = false>
; __device__ __forceinline__ void gemm_phase(PG8_LAS unsigned char* lds, const Gemm g, const Sched& S, const Epi& E) {
;     ...
;             PG8_LDA(At, 1, 1); PG8_STAGE(PG8_SB(1, 0), b3, voffB); PG8_STAGE(PG8_SB(1, 1), b3 + hstep, voffB); PG8_STAGE(PG8_SA(1, 0), a3, voffA);
;             PG8_WAIT_V(8); PG8_WAIT_L(0); PG8_BAR; PG8_MMA(1, 0, At, B0); PG8_MMA(1, 1, At, B1); PG8_BAR; PG8_SCHED;
;     ...
;         if constexpr (ALIGN_EPI) { if (wr == 0) PG8_BAR; }
	s_add_i32 s48, s75, s52
	v_lshl_add_u64 v[146:147], v[146:147], 0, s[12:13]
	s_mov_b32 m0, s48
	ds_read_b128 v[188:191], v154 offset:49152
	ds_read_b128 v[192:195], v154 offset:50176
	ds_read_b128 v[198:201], v154 offset:51200
	ds_read_b128 v[202:205], v154 offset:52224
	ds_read_b128 v[206:209], v154 offset:53248
	ds_read_b128 v[210:213], v154 offset:54272
	ds_read_b128 v[214:217], v154 offset:55296
	ds_read_b128 v[218:221], v154 offset:56320
	global_load_lds_dwordx4 v[146:147], off
	s_add_i32 m0, s48, 0x2000
	s_add_u32 s46, s46, 0x100080
	v_lshl_add_u64 v[146:147], v[222:223], 0, s[12:13]
	s_addc_u32 s47, s47, 0
	s_add_i32 s48, s76, s52
	global_load_lds_dwordx4 v[146:147], off
	v_lshl_add_u64 v[146:147], s[46:47], 0, v[134:135]
	s_mov_b32 m0, s48
	s_nop 0
	global_load_lds_dwordx4 v[146:147], off
	v_lshl_add_u64 v[146:147], s[46:47], 0, v[130:131]
	s_add_i32 m0, s48, 0x2000
	s_nop 0
	global_load_lds_dwordx4 v[146:147], off
	v_lshl_add_u64 v[146:147], v[224:225], 0, s[12:13]
	s_mov_b32 m0, s59
	s_nop 0
	global_load_lds_dwordx4 v[146:147], off
	v_lshl_add_u64 v[146:147], v[226:227], 0, s[12:13]
	s_mov_b32 m0, s60
	s_nop 0
	global_load_lds_dwordx4 v[146:147], off
	s_waitcnt vmcnt(8)
	s_waitcnt lgkmcnt(0)
	s_setprio 0
	s_barrier
	v_mfma_f32_16x16x32_bf16 v[58:61], v[156:159], v[188:191], v[58:61]
	v_mfma_f32_16x16x32_bf16 v[50:53], v[164:167], v[188:191], v[50:53]
	v_mfma_f32_16x16x32_bf16 v[42:45], v[156:159], v[198:201], v[42:45]
	v_mfma_f32_16x16x32_bf16 v[34:37], v[164:167], v[198:201], v[34:37]
	v_mfma_f32_16x16x32_bf16 v[26:29], v[156:159], v[206:209], v[26:29]
	v_mfma_f32_16x16x32_bf16 v[18:21], v[164:167], v[206:209], v[18:21]
	v_mfma_f32_16x16x32_bf16 v[10:13], v[156:159], v[214:217], v[10:13]
	v_mfma_f32_16x16x32_bf16 v[6:9], v[164:167], v[214:217], v[6:9]
	v_mfma_f32_16x16x32_bf16 v[58:61], v[160:163], v[192:195], v[58:61]
	v_mfma_f32_16x16x32_bf16 v[50:53], v[168:171], v[192:195], v[50:53]
	v_mfma_f32_16x16x32_bf16 v[42:45], v[160:163], v[202:205], v[42:45]
	v_mfma_f32_16x16x32_bf16 v[34:37], v[168:171], v[202:205], v[34:37]
	v_mfma_f32_16x16x32_bf16 v[26:29], v[160:163], v[210:213], v[26:29]
	v_mfma_f32_16x16x32_bf16 v[18:21], v[168:171], v[210:213], v[18:21]
	v_mfma_f32_16x16x32_bf16 v[10:13], v[160:163], v[218:221], v[10:13]
	v_mfma_f32_16x16x32_bf16 v[6:9], v[168:171], v[218:221], v[6:9]
	s_setprio 0
	s_setprio 0
	v_mfma_f32_16x16x32_bf16 v[62:65], v[172:175], v[188:191], v[62:65]
	v_mfma_f32_16x16x32_bf16 v[54:57], v[180:183], v[188:191], v[54:57]
	v_mfma_f32_16x16x32_bf16 v[46:49], v[172:175], v[198:201], v[46:49]
	v_mfma_f32_16x16x32_bf16 v[38:41], v[180:183], v[198:201], v[38:41]
	v_mfma_f32_16x16x32_bf16 v[30:33], v[172:175], v[206:209], v[30:33]
	v_mfma_f32_16x16x32_bf16 v[22:25], v[180:183], v[206:209], v[22:25]
	v_mfma_f32_16x16x32_bf16 v[14:17], v[172:175], v[214:217], v[14:17]
	v_mfma_f32_16x16x32_bf16 v[2:5], v[180:183], v[214:217], v[2:5]
	v_mfma_f32_16x16x32_bf16 v[62:65], v[176:179], v[192:195], v[62:65]
	v_mfma_f32_16x16x32_bf16 v[54:57], v[184:187], v[192:195], v[54:57]
	v_mfma_f32_16x16x32_bf16 v[46:49], v[176:179], v[202:205], v[46:49]
	v_mfma_f32_16x16x32_bf16 v[38:41], v[184:187], v[202:205], v[38:41]
	v_mfma_f32_16x16x32_bf16 v[30:33], v[176:179], v[210:213], v[30:33]
	v_mfma_f32_16x16x32_bf16 v[22:25], v[184:187], v[210:213], v[22:25]
	v_mfma_f32_16x16x32_bf16 v[14:17], v[176:179], v[218:221], v[14:17]
	v_mfma_f32_16x16x32_bf16 v[2:5], v[184:187], v[218:221], v[2:5]
	s_setprio 1
	s_barrier
	s_add_i32 s74, s74, 2
	s_add_u32 s44, s44, 0x100
	s_addc_u32 s45, s45, 0
	s_add_u32 s72, s72, 0x100
	s_addc_u32 s73, s73, 0
	s_cmp_gt_u32 s74, 61
	s_cbranch_scc0 .LBB0_881
	s_and_b64 vcc, exec, s[16:17]
	s_cbranch_vccz .LBB0_884
	s_barrier

; #define PG8_STAGE(bufoff, gbase, voff) do { _Pragma("unroll") for (int _i = 0; _i < 2; ++_i) \
;         __builtin_amdgcn_global_load_lds((const unsigned*)((const char*)(gbase) + (voff)[_i]), (PG8_LAS unsigned*)(lds + (bufoff) + ldsw + _i * 8192), 16, 0, 0); } while (0)
; #define PG8_LDA(dst, b, h) do { _Pragma("unroll") for (int m = 0; m < 4; ++m) _Pragma("unroll") for (int k = 0; k < 2; ++k) dst[m][k] = *(const PG8_LAS bf16x8*)(lds + PG8_SA(b, h) + aoff + m * 2048 + k * 1024); } while (0)
; #define PG8_LDB(dst, b, h) do { _Pragma("unroll") for (int n = 0; n < 2; ++n) _Pragma("unroll") for (int k = 0; k < 2; ++k) dst[n][k] = *(const PG8_LAS bf16x8*)(lds + PG8_SB(b, h) + boff + n * 2048 + k * 1024); } while (0)
; #define PG8_MMA(ai, bj, At, Bt) do { __builtin_amdgcn_s_setprio(1); _Pragma("unroll") for (int m = 0; m < 4; ++m) _Pragma("unroll") for (int n = 0; n < 2; ++n) _Pragma("unroll") for (int k = 0; k < 2; ++k) \
;         acc[ai][bj][m][n] = __builtin_amdgcn_mfma_f32_16x16x32_bf16(Bt[n][k], At[m][k], acc[ai][bj][m][n], 0, 0, 0); __builtin_amdgcn_s_setprio(0); } while (0)
; #define PG8_WAIT_V(n) asm volatile("s_waitcnt vmcnt(" #n ")" ::: "memory")
; template <class Epi, class Sched, bool ALIGN_EPI = false, bool SP2 = false>
; __device__ __forceinline__ void gemm_phase(PG8_LAS unsigned char* lds, const Gemm g, const Sched& S, const Epi& E) {
;     ...
;             PG8_LDB(B0, 0, 0); PG8_LDB(B1, 0, 1); PG8_SCHED; PG8_LDA(At, 0, 0); PG8_STAGE(PG8_SA(1, 1), a1 + hstep, voffA);
;             PG8_WAIT_V(8); PG8_WAIT_L(0); PG8_BAR; PG8_MMA(0, 0, At, B0); PG8_MMA(0, 1, At, B1); PG8_BAR; PG8_SCHED;
;             PG8_LDA(At, 0, 1); PG8_STAGE(PG8_SB(0, 0), b2, voffB); PG8_STAGE(PG8_SB(0, 1), b2 + hstep, voffB); PG8_STAGE(PG8_SA(0, 0), a2, voffA);
;             PG8_WAIT_V(8); PG8_WAIT_L(0); PG8_BAR; PG8_MMA(1, 0, At, B0); PG8_MMA(1, 1, At, B1); PG8_BAR; PG8_SCHED;
;             PG8_LDB(B0, 1, 0); PG8_LDB(B1, 1, 1); PG8_SCHED; PG8_LDA(At, 1, 0); PG8_STAGE(PG8_SA(0, 1), a2 + hstep, voffA);
;             PG8_WAIT_V(8); PG8_WAIT_L(0); PG8_BAR; PG8_MMA(0, 0, At, B0); PG8_MMA(0, 1, At, B1); PG8_BAR; PG8_SCHED;
;             PG8_LDA(At, 1, 1); PG8_STAGE(PG8_SB(1, 0), b3, voffB); PG8_STAGE(PG8_SB(1, 1), b3 + hstep, voffB); PG8_STAGE(PG8_SA(1, 0), a3, voffA);
;             PG8_WAIT_V(8); PG8_WAIT_L(0); PG8_BAR; PG8_MMA(1, 0, At, B0); PG8_MMA(1, 1, At, B1); PG8_BAR; PG8_SCHED;
.LBB0_984:
	ds_read_b128 v[146:149], v160
	ds_read_b128 v[164:167], v160 offset:1024
	ds_read_b128 v[168:171], v160 offset:2048
	ds_read_b128 v[172:175], v160 offset:3072
	ds_read_b128 v[176:179], v161
	ds_read_b128 v[180:183], v161 offset:1024
	ds_read_b128 v[184:187], v161 offset:2048
	ds_read_b128 v[188:191], v161 offset:3072
	s_add_u32 s44, s42, 0xffd50080
	s_addc_u32 s45, s43, -1
	s_cmpk_eq_i32 s71, 0xa8
	s_cselect_b32 s47, s7, s45
	s_cselect_b32 s46, s6, s44
	s_cselect_b32 s45, s41, s70
	s_cselect_b32 s44, s40, s69
	v_lshl_add_u64 v[226:227], s[42:43], 0, v[138:139]
	s_add_i32 m0, s52, 0xc000
	ds_read_b128 v[192:195], v162
	ds_read_b128 v[198:201], v162 offset:1024
	ds_read_b128 v[202:205], v162 offset:2048
	ds_read_b128 v[206:209], v162 offset:3072
	ds_read_b128 v[210:213], v162 offset:4096
	ds_read_b128 v[214:217], v162 offset:5120
	ds_read_b128 v[218:221], v162 offset:6144
	ds_read_b128 v[222:225], v162 offset:7168
	global_load_lds_dwordx4 v[226:227], off
	v_lshl_add_u64 v[226:227], s[42:43], 0, v[140:141]
	s_add_i32 m0, s52, 0xe000
	s_nop 0
	global_load_lds_dwordx4 v[226:227], off
	s_waitcnt vmcnt(8)
	s_waitcnt lgkmcnt(0)
	s_setprio 0
	s_barrier
	v_mfma_f32_16x16x32_bf16 v[126:129], v[146:149], v[192:195], v[126:129]
	v_mfma_f32_16x16x32_bf16 v[122:125], v[168:171], v[192:195], v[122:125]
	v_mfma_f32_16x16x32_bf16 v[110:113], v[146:149], v[202:205], v[110:113]
	v_mfma_f32_16x16x32_bf16 v[106:109], v[168:171], v[202:205], v[106:109]
	v_mfma_f32_16x16x32_bf16 v[94:97], v[146:149], v[210:213], v[94:97]
	v_mfma_f32_16x16x32_bf16 v[90:93], v[168:171], v[210:213], v[90:93]
	v_mfma_f32_16x16x32_bf16 v[78:81], v[146:149], v[218:221], v[78:81]
	v_mfma_f32_16x16x32_bf16 v[74:77], v[168:171], v[218:221], v[74:77]
	v_mfma_f32_16x16x32_bf16 v[126:129], v[164:167], v[198:201], v[126:129]
	v_mfma_f32_16x16x32_bf16 v[122:125], v[172:175], v[198:201], v[122:125]
	v_mfma_f32_16x16x32_bf16 v[110:113], v[164:167], v[206:209], v[110:113]
	v_mfma_f32_16x16x32_bf16 v[106:109], v[172:175], v[206:209], v[106:109]
	v_mfma_f32_16x16x32_bf16 v[94:97], v[164:167], v[214:217], v[94:97]
	v_mfma_f32_16x16x32_bf16 v[90:93], v[172:175], v[214:217], v[90:93]
	v_mfma_f32_16x16x32_bf16 v[78:81], v[164:167], v[222:225], v[78:81]
	v_mfma_f32_16x16x32_bf16 v[74:77], v[172:175], v[222:225], v[74:77]
	s_setprio 0
	s_setprio 0
	v_mfma_f32_16x16x32_bf16 v[118:121], v[176:179], v[192:195], v[118:121]
	v_mfma_f32_16x16x32_bf16 v[114:117], v[184:187], v[192:195], v[114:117]
	v_mfma_f32_16x16x32_bf16 v[102:105], v[176:179], v[202:205], v[102:105]
	v_mfma_f32_16x16x32_bf16 v[98:101], v[184:187], v[202:205], v[98:101]
	v_mfma_f32_16x16x32_bf16 v[86:89], v[176:179], v[210:213], v[86:89]
	v_mfma_f32_16x16x32_bf16 v[82:85], v[184:187], v[210:213], v[82:85]
	v_mfma_f32_16x16x32_bf16 v[70:73], v[176:179], v[218:221], v[70:73]
	v_mfma_f32_16x16x32_bf16 v[66:69], v[184:187], v[218:221], v[66:69]
	v_mfma_f32_16x16x32_bf16 v[118:121], v[180:183], v[198:201], v[118:121]
	v_mfma_f32_16x16x32_bf16 v[114:117], v[188:191], v[198:201], v[114:117]
	v_mfma_f32_16x16x32_bf16 v[102:105], v[180:183], v[206:209], v[102:105]
	v_mfma_f32_16x16x32_bf16 v[98:101], v[188:191], v[206:209], v[98:101]
	v_mfma_f32_16x16x32_bf16 v[86:89], v[180:183], v[214:217], v[86:89]
	v_mfma_f32_16x16x32_bf16 v[82:85], v[188:191], v[214:217], v[82:85]
	v_mfma_f32_16x16x32_bf16 v[70:73], v[180:183], v[222:225], v[70:73]
	v_mfma_f32_16x16x32_bf16 v[66:69], v[188:191], v[222:225], v[66:69]
	s_setprio 1
	s_barrier
	s_add_i32 s72, s62, s51
	v_lshl_add_u64 v[226:227], s[44:45], 0, v[132:133]
	s_mov_b32 m0, s72
	ds_read_b128 v[192:195], v162 offset:16384
	ds_read_b128 v[198:201], v162 offset:17408
	ds_read_b128 v[202:205], v162 offset:18432
	ds_read_b128 v[206:209], v162 offset:19456
	ds_read_b128 v[210:213], v162 offset:20480
	ds_read_b128 v[214:217], v162 offset:21504
	ds_read_b128 v[218:221], v162 offset:22528
	ds_read_b128 v[222:225], v162 offset:23552
	global_load_lds_dwordx4 v[226:227], off
	s_add_i32 m0, s72, 0x2000
	s_add_u32 s72, s44, 0x2b0000
	v_lshl_add_u64 v[228:229], s[44:45], 0, v[136:137]
	s_addc_u32 s73, s45, 0
	s_add_i32 s74, s63, s51
	global_load_lds_dwordx4 v[228:229], off
	v_lshl_add_u64 v[230:231], s[72:73], 0, v[132:133]
	s_mov_b32 m0, s74
	v_lshl_add_u64 v[232:233], s[46:47], 0, v[134:135]
	global_load_lds_dwordx4 v[230:231], off
	v_lshl_add_u64 v[230:231], s[72:73], 0, v[136:137]
	s_add_i32 m0, s74, 0x2000
	s_nop 0
	global_load_lds_dwordx4 v[230:231], off
	v_lshl_add_u64 v[230:231], s[46:47], 0, v[130:131]
	s_mov_b32 m0, s52
	s_nop 0
	global_load_lds_dwordx4 v[230:231], off
	s_mov_b32 m0, s53
	s_nop 0
	global_load_lds_dwordx4 v[232:233], off
	s_waitcnt vmcnt(8)
	s_waitcnt lgkmcnt(0)
	s_setprio 0
	s_barrier
; #define PG8_STAGE(bufoff, gbase, voff) do { _Pragma("unroll") for (int _i = 0; _i < 2; ++_i) \
;         __builtin_amdgcn_global_load_lds((const unsigned*)((const char*)(gbase) + (voff)[_i]), (PG8_LAS unsigned*)(lds + (bufoff) + ldsw + _i * 8192), 16, 0, 0); } while (0)
; #define PG8_LDA(dst, b, h) do { _Pragma("unroll") for (int m = 0; m < 4; ++m) _Pragma("unroll") for (int k = 0; k < 2; ++k) dst[m][k] = *(const PG8_LAS bf16x8*)(lds + PG8_SA(b, h) + aoff + m * 2048 + k * 1024); } while (0)
; #define PG8_LDB(dst, b, h) do { _Pragma("unroll") for (int n = 0; n < 2; ++n) _Pragma("unroll") for (int k = 0; k < 2; ++k) dst[n][k] = *(const PG8_LAS bf16x8*)(lds + PG8_SB(b, h) + boff + n * 2048 + k * 1024); } while (0)
; #define PG8_MMA(ai, bj, At, Bt) do { __builtin_amdgcn_s_setprio(1); _Pragma("unroll") for (int m = 0; m < 4; ++m) _Pragma("unroll") for (int n = 0; n < 2; ++n) _Pragma("unroll") for (int k = 0; k < 2; ++k) \
;         acc[ai][bj][m][n] = __builtin_amdgcn_mfma_f32_16x16x32_bf16(Bt[n][k], At[m][k], acc[ai][bj][m][n], 0, 0, 0); __builtin_amdgcn_s_setprio(0); } while (0)
; #define PG8_WAIT_V(n) asm volatile("s_waitcnt vmcnt(" #n ")" ::: "memory")
; #define PG8_WAIT_L(n) asm volatile("s_waitcnt lgkmcnt(" #n ")" ::: "memory")
; #define PG8_BAR __builtin_amdgcn_s_barrier()
; #define PG8_SCHED __builtin_amdgcn_sched_barrier(0)
; template <class Epi, class Sched, bool ALIGN_EPI = false, bool SP2 = false>
; __device__ __forceinline__ void gemm_phase(PG8_LAS unsigned char* lds, const Gemm g, const Sched& S, const Epi& E) {
;     ...
;             PG8_WAIT_V(8); PG8_WAIT_L(0); PG8_BAR; PG8_MMA(1, 0, At, B0); PG8_MMA(1, 1, At, B1); PG8_BAR; PG8_SCHED;
;             PG8_LDB(B0, 1, 0); PG8_LDB(B1, 1, 1); PG8_SCHED; PG8_LDA(At, 1, 0); PG8_STAGE(PG8_SA(0, 1), a2 + hstep, voffA);
;             PG8_WAIT_V(8); PG8_WAIT_L(0); PG8_BAR; PG8_MMA(0, 0, At, B0); PG8_MMA(0, 1, At, B1); PG8_BAR; PG8_SCHED;
	v_mfma_f32_16x16x32_bf16 v[62:65], v[146:149], v[192:195], v[62:65]
	v_mfma_f32_16x16x32_bf16 v[58:61], v[168:171], v[192:195], v[58:61]
	v_mfma_f32_16x16x32_bf16 v[46:49], v[146:149], v[202:205], v[46:49]
	v_mfma_f32_16x16x32_bf16 v[42:45], v[168:171], v[202:205], v[42:45]
	v_mfma_f32_16x16x32_bf16 v[30:33], v[146:149], v[210:213], v[30:33]
	v_mfma_f32_16x16x32_bf16 v[26:29], v[168:171], v[210:213], v[26:29]
	v_mfma_f32_16x16x32_bf16 v[14:17], v[146:149], v[218:221], v[14:17]
	v_mfma_f32_16x16x32_bf16 v[10:13], v[168:171], v[218:221], v[10:13]
	v_mfma_f32_16x16x32_bf16 v[62:65], v[164:167], v[198:201], v[62:65]
	v_mfma_f32_16x16x32_bf16 v[58:61], v[172:175], v[198:201], v[58:61]
	v_mfma_f32_16x16x32_bf16 v[46:49], v[164:167], v[206:209], v[46:49]
	v_mfma_f32_16x16x32_bf16 v[42:45], v[172:175], v[206:209], v[42:45]
	v_mfma_f32_16x16x32_bf16 v[30:33], v[164:167], v[214:217], v[30:33]
	v_mfma_f32_16x16x32_bf16 v[26:29], v[172:175], v[214:217], v[26:29]
	v_mfma_f32_16x16x32_bf16 v[14:17], v[164:167], v[222:225], v[14:17]
	v_mfma_f32_16x16x32_bf16 v[10:13], v[172:175], v[222:225], v[10:13]
	s_setprio 0
	s_setprio 0
	v_mfma_f32_16x16x32_bf16 v[54:57], v[176:179], v[192:195], v[54:57]
	v_mfma_f32_16x16x32_bf16 v[50:53], v[184:187], v[192:195], v[50:53]
	v_mfma_f32_16x16x32_bf16 v[38:41], v[176:179], v[202:205], v[38:41]
	v_mfma_f32_16x16x32_bf16 v[34:37], v[184:187], v[202:205], v[34:37]
	v_mfma_f32_16x16x32_bf16 v[22:25], v[176:179], v[210:213], v[22:25]
	v_mfma_f32_16x16x32_bf16 v[18:21], v[184:187], v[210:213], v[18:21]
	v_mfma_f32_16x16x32_bf16 v[6:9], v[176:179], v[218:221], v[6:9]
	v_mfma_f32_16x16x32_bf16 v[2:5], v[184:187], v[218:221], v[2:5]
	v_mfma_f32_16x16x32_bf16 v[54:57], v[180:183], v[198:201], v[54:57]
	v_mfma_f32_16x16x32_bf16 v[50:53], v[188:191], v[198:201], v[50:53]
	v_mfma_f32_16x16x32_bf16 v[38:41], v[180:183], v[206:209], v[38:41]
	v_mfma_f32_16x16x32_bf16 v[34:37], v[188:191], v[206:209], v[34:37]
	v_mfma_f32_16x16x32_bf16 v[22:25], v[180:183], v[214:217], v[22:25]
	v_mfma_f32_16x16x32_bf16 v[18:21], v[188:191], v[214:217], v[18:21]
	v_mfma_f32_16x16x32_bf16 v[6:9], v[180:183], v[222:225], v[6:9]
	v_mfma_f32_16x16x32_bf16 v[2:5], v[188:191], v[222:225], v[2:5]
	s_setprio 1
	s_barrier
	s_add_i32 s72, 0, 0x18000
	s_add_i32 s73, 0, 0x1c000
	v_add_u32_e32 v172, s72, v151
	v_add_u32_e32 v188, s73, v151
	ds_read_b128 v[146:149], v172
	ds_read_b128 v[164:167], v172 offset:1024
	ds_read_b128 v[168:171], v172 offset:2048
	ds_read_b128 v[172:175], v172 offset:3072
	ds_read_b128 v[176:179], v188
	ds_read_b128 v[180:183], v188 offset:1024
	ds_read_b128 v[184:187], v188 offset:2048
	ds_read_b128 v[188:191], v188 offset:3072
	s_add_u32 s46, s46, 0x2b0000
	s_addc_u32 s47, s47, 0
	s_mov_b32 m0, s54
	v_lshl_add_u64 v[234:235], s[46:47], 0, v[130:131]
	ds_read_b128 v[192:195], v162 offset:32768
	ds_read_b128 v[198:201], v162 offset:33792
	ds_read_b128 v[202:205], v162 offset:34816
	ds_read_b128 v[206:209], v162 offset:35840
	ds_read_b128 v[210:213], v162 offset:36864
	ds_read_b128 v[214:217], v162 offset:37888
	ds_read_b128 v[218:221], v162 offset:38912
	ds_read_b128 v[222:225], v162 offset:39936
	global_load_lds_dwordx4 v[234:235], off
	v_lshl_add_u64 v[234:235], s[46:47], 0, v[134:135]
	s_mov_b32 m0, s55
	s_nop 0
	global_load_lds_dwordx4 v[234:235], off
	s_waitcnt vmcnt(8)
	s_waitcnt lgkmcnt(0)
	s_setprio 0
	s_barrier
	v_mfma_f32_16x16x32_bf16 v[126:129], v[146:149], v[192:195], v[126:129]
	v_mfma_f32_16x16x32_bf16 v[122:125], v[168:171], v[192:195], v[122:125]
	v_mfma_f32_16x16x32_bf16 v[110:113], v[146:149], v[202:205], v[110:113]
	v_mfma_f32_16x16x32_bf16 v[106:109], v[168:171], v[202:205], v[106:109]
	v_mfma_f32_16x16x32_bf16 v[94:97], v[146:149], v[210:213], v[94:97]
	v_mfma_f32_16x16x32_bf16 v[90:93], v[168:171], v[210:213], v[90:93]
	v_mfma_f32_16x16x32_bf16 v[78:81], v[146:149], v[218:221], v[78:81]
	v_mfma_f32_16x16x32_bf16 v[74:77], v[168:171], v[218:221], v[74:77]
	v_mfma_f32_16x16x32_bf16 v[126:129], v[164:167], v[198:201], v[126:129]
	v_mfma_f32_16x16x32_bf16 v[122:125], v[172:175], v[198:201], v[122:125]
	v_mfma_f32_16x16x32_bf16 v[110:113], v[164:167], v[206:209], v[110:113]
	v_mfma_f32_16x16x32_bf16 v[106:109], v[172:175], v[206:209], v[106:109]
	v_mfma_f32_16x16x32_bf16 v[94:97], v[164:167], v[214:217], v[94:97]
	v_mfma_f32_16x16x32_bf16 v[90:93], v[172:175], v[214:217], v[90:93]
	v_mfma_f32_16x16x32_bf16 v[78:81], v[164:167], v[222:225], v[78:81]
	v_mfma_f32_16x16x32_bf16 v[74:77], v[172:175], v[222:225], v[74:77]
	s_setprio 0
	s_setprio 0
	v_mfma_f32_16x16x32_bf16 v[118:121], v[176:179], v[192:195], v[118:121]
	v_mfma_f32_16x16x32_bf16 v[114:117], v[184:187], v[192:195], v[114:117]
	v_mfma_f32_16x16x32_bf16 v[102:105], v[176:179], v[202:205], v[102:105]
	v_mfma_f32_16x16x32_bf16 v[98:101], v[184:187], v[202:205], v[98:101]
	v_mfma_f32_16x16x32_bf16 v[86:89], v[176:179], v[210:213], v[86:89]
	v_mfma_f32_16x16x32_bf16 v[82:85], v[184:187], v[210:213], v[82:85]
	v_mfma_f32_16x16x32_bf16 v[70:73], v[176:179], v[218:221], v[70:73]
	v_mfma_f32_16x16x32_bf16 v[66:69], v[184:187], v[218:221], v[66:69]
	v_mfma_f32_16x16x32_bf16 v[118:121], v[180:183], v[198:201], v[118:121]
	v_mfma_f32_16x16x32_bf16 v[114:117], v[188:191], v[198:201], v[114:117]
	v_mfma_f32_16x16x32_bf16 v[102:105], v[180:183], v[206:209], v[102:105]
	v_mfma_f32_16x16x32_bf16 v[98:101], v[188:191], v[206:209], v[98:101]
	v_mfma_f32_16x16x32_bf16 v[86:89], v[180:183], v[214:217], v[86:89]
	v_mfma_f32_16x16x32_bf16 v[82:85], v[188:191], v[214:217], v[82:85]
	v_mfma_f32_16x16x32_bf16 v[70:73], v[180:183], v[222:225], v[70:73]
	v_mfma_f32_16x16x32_bf16 v[66:69], v[188:191], v[222:225], v[66:69]
	s_setprio 1
	s_barrier
; #define PG8_STAGE(bufoff, gbase, voff) do { _Pragma("unroll") for (int _i = 0; _i < 2; ++_i) \
;         __builtin_amdgcn_global_load_lds((const unsigned*)((const char*)(gbase) + (voff)[_i]), (PG8_LAS unsigned*)(lds + (bufoff) + ldsw + _i * 8192), 16, 0, 0); } while (0)
; #define PG8_LDA(dst, b, h) do { _Pragma("unroll") for (int m = 0; m < 4; ++m) _Pragma("unroll") for (int k = 0; k < 2; ++k) dst[m][k] = *(const PG8_LAS bf16x8*)(lds + PG8_SA(b, h) + aoff + m * 2048 + k * 1024); } while (0)
; #define PG8_MMA(ai, bj, At, Bt) do { __builtin_amdgcn_s_setprio(1); _Pragma("unroll") for (int m = 0; m < 4; ++m) _Pragma("unroll") for (int n = 0; n < 2; ++n) _Pragma("unroll") for (int k = 0; k < 2; ++k) \
;         acc[ai][bj][m][n] = __builtin_amdgcn_mfma_f32_16x16x32_bf16(Bt[n][k], At[m][k], acc[ai][bj][m][n], 0, 0, 0); __builtin_amdgcn_s_setprio(0); } while (0)
; #define PG8_WAIT_V(n) asm volatile("s_waitcnt vmcnt(" #n ")" ::: "memory")
; #define PG8_WAIT_L(n) asm volatile("s_waitcnt lgkmcnt(" #n ")" ::: "memory")
; #define PG8_BAR __builtin_amdgcn_s_barrier()
; #define PG8_SCHED __builtin_amdgcn_sched_barrier(0)
; template <class Epi, class Sched, bool ALIGN_EPI = false, bool SP2 = false>
; __device__ __forceinline__ void gemm_phase(PG8_LAS unsigned char* lds, const Gemm g, const Sched& S, const Epi& E) {
;     ...
;         for (int t = 0; t < nt; t += 2) {
;             const bool last = (t == nt - 2);
;     ...
;             PG8_LDA(At, 1, 1); PG8_STAGE(PG8_SB(1, 0), b3, voffB); PG8_STAGE(PG8_SB(1, 1), b3 + hstep, voffB); PG8_STAGE(PG8_SA(1, 0), a3, voffA);
;             PG8_WAIT_V(8); PG8_WAIT_L(0); PG8_BAR; PG8_MMA(1, 0, At, B0); PG8_MMA(1, 1, At, B1); PG8_BAR; PG8_SCHED;
	s_add_i32 s46, s72, s51
	v_lshl_add_u64 v[226:227], v[226:227], 0, s[36:37]
	s_mov_b32 m0, s46
	ds_read_b128 v[192:195], v162 offset:49152
	ds_read_b128 v[198:201], v162 offset:50176
	ds_read_b128 v[202:205], v162 offset:51200
	ds_read_b128 v[206:209], v162 offset:52224
	ds_read_b128 v[210:213], v162 offset:53248
	ds_read_b128 v[214:217], v162 offset:54272
	ds_read_b128 v[218:221], v162 offset:55296
	ds_read_b128 v[222:225], v162 offset:56320
	global_load_lds_dwordx4 v[226:227], off
	s_add_i32 m0, s46, 0x2000
	s_add_u32 s44, s44, 0x2b0080
	v_lshl_add_u64 v[226:227], v[228:229], 0, s[36:37]
	s_addc_u32 s45, s45, 0
	s_add_i32 s46, s73, s51
	global_load_lds_dwordx4 v[226:227], off
	v_lshl_add_u64 v[226:227], s[44:45], 0, v[132:133]
	s_mov_b32 m0, s46
	s_nop 0
	global_load_lds_dwordx4 v[226:227], off
	v_lshl_add_u64 v[226:227], s[44:45], 0, v[136:137]
	s_add_i32 m0, s46, 0x2000
	s_nop 0
	global_load_lds_dwordx4 v[226:227], off
	v_lshl_add_u64 v[226:227], v[230:231], 0, s[36:37]
	s_mov_b32 m0, s57
	s_nop 0
	global_load_lds_dwordx4 v[226:227], off
	v_lshl_add_u64 v[226:227], v[232:233], 0, s[36:37]
	s_mov_b32 m0, s58
	s_nop 0
	global_load_lds_dwordx4 v[226:227], off
	s_waitcnt vmcnt(8)
	s_waitcnt lgkmcnt(0)
	s_setprio 0
	s_barrier
	v_mfma_f32_16x16x32_bf16 v[62:65], v[146:149], v[192:195], v[62:65]
	v_mfma_f32_16x16x32_bf16 v[58:61], v[168:171], v[192:195], v[58:61]
	v_mfma_f32_16x16x32_bf16 v[46:49], v[146:149], v[202:205], v[46:49]
	v_mfma_f32_16x16x32_bf16 v[42:45], v[168:171], v[202:205], v[42:45]
	v_mfma_f32_16x16x32_bf16 v[30:33], v[146:149], v[210:213], v[30:33]
	v_mfma_f32_16x16x32_bf16 v[26:29], v[168:171], v[210:213], v[26:29]
	v_mfma_f32_16x16x32_bf16 v[14:17], v[146:149], v[218:221], v[14:17]
	v_mfma_f32_16x16x32_bf16 v[10:13], v[168:171], v[218:221], v[10:13]
	v_mfma_f32_16x16x32_bf16 v[62:65], v[164:167], v[198:201], v[62:65]
	v_mfma_f32_16x16x32_bf16 v[58:61], v[172:175], v[198:201], v[58:61]
	v_mfma_f32_16x16x32_bf16 v[46:49], v[164:167], v[206:209], v[46:49]
	v_mfma_f32_16x16x32_bf16 v[42:45], v[172:175], v[206:209], v[42:45]
	v_mfma_f32_16x16x32_bf16 v[30:33], v[164:167], v[214:217], v[30:33]
	v_mfma_f32_16x16x32_bf16 v[26:29], v[172:175], v[214:217], v[26:29]
	v_mfma_f32_16x16x32_bf16 v[14:17], v[164:167], v[222:225], v[14:17]
	v_mfma_f32_16x16x32_bf16 v[10:13], v[172:175], v[222:225], v[10:13]
	s_setprio 0
	s_setprio 0
	v_mfma_f32_16x16x32_bf16 v[54:57], v[176:179], v[192:195], v[54:57]
	v_mfma_f32_16x16x32_bf16 v[50:53], v[184:187], v[192:195], v[50:53]
	v_mfma_f32_16x16x32_bf16 v[38:41], v[176:179], v[202:205], v[38:41]
	v_mfma_f32_16x16x32_bf16 v[34:37], v[184:187], v[202:205], v[34:37]
	v_mfma_f32_16x16x32_bf16 v[22:25], v[176:179], v[210:213], v[22:25]
	v_mfma_f32_16x16x32_bf16 v[18:21], v[184:187], v[210:213], v[18:21]
	v_mfma_f32_16x16x32_bf16 v[6:9], v[176:179], v[218:221], v[6:9]
	v_mfma_f32_16x16x32_bf16 v[2:5], v[184:187], v[218:221], v[2:5]
	v_mfma_f32_16x16x32_bf16 v[54:57], v[180:183], v[198:201], v[54:57]
	v_mfma_f32_16x16x32_bf16 v[50:53], v[188:191], v[198:201], v[50:53]
	v_mfma_f32_16x16x32_bf16 v[38:41], v[180:183], v[206:209], v[38:41]
	v_mfma_f32_16x16x32_bf16 v[34:37], v[188:191], v[206:209], v[34:37]
	v_mfma_f32_16x16x32_bf16 v[22:25], v[180:183], v[214:217], v[22:25]
	v_mfma_f32_16x16x32_bf16 v[18:21], v[188:191], v[214:217], v[18:21]
	v_mfma_f32_16x16x32_bf16 v[6:9], v[180:183], v[222:225], v[6:9]
	v_mfma_f32_16x16x32_bf16 v[2:5], v[188:191], v[222:225], v[2:5]
	s_setprio 1
	s_barrier
	s_add_i32 s71, s71, 2
	s_add_u32 s42, s42, 0x100
	s_addc_u32 s43, s43, 0
	s_add_u32 s69, s69, 0x100
	s_addc_u32 s70, s70, 0
	s_cmpk_gt_u32 s71, 0xa9
	s_cbranch_scc0 .LBB0_984
	s_and_b64 vcc, exec, s[38:39]
	s_cbranch_vccz .LBB0_987
	s_barrier
